# code placement: one s_nop 0 of padding where needed so that every 16-MFMA block of the four GEMM K-loops starts 8-byte aligned (9 pads)
# speedup vs baseline: 1.0016x; 1.0016x over previous
; #define PG8_STAGE(bufoff, gbase, voff) do { _Pragma("unroll") for (int _i = 0; _i < 2; ++_i) \
;         __builtin_amdgcn_global_load_lds((const unsigned*)((const char*)(gbase) + (voff)[_i]), (LAS unsigned*)(lds + (bufoff) + ldsw + _i * 8192), 16, 0, 0); } while (0)
; #define PG8_LDA(dst, b, h) do { _Pragma("unroll") for (int m = 0; m < 4; ++m) _Pragma("unroll") for (int k = 0; k < 2; ++k) dst[m][k] = *(const LAS bf16x8*)(lds + PG8_SA(b, h) + aoff + m * 2048 + k * 1024); } while (0)
; #define PG8_LDB(dst, b, h) do { _Pragma("unroll") for (int n = 0; n < 2; ++n) _Pragma("unroll") for (int k = 0; k < 2; ++k) dst[n][k] = *(const LAS bf16x8*)(lds + PG8_SB(b, h) + boff + n * 2048 + k * 1024); } while (0)
; #define PG8_MMA(ai, bj, At, Bt) do { __builtin_amdgcn_s_setprio(1); _Pragma("unroll") for (int m = 0; m < 4; ++m) _Pragma("unroll") for (int n = 0; n < 2; ++n) _Pragma("unroll") for (int k = 0; k < 2; ++k) \
;         acc[ai][bj][m][n] = __builtin_amdgcn_mfma_f32_16x16x32_bf16(Bt[n][k], At[m][k], acc[ai][bj][m][n], 0, 0, 0); __builtin_amdgcn_s_setprio(0); } while (0)
; #define PG8_WAIT_V(n) asm volatile("s_waitcnt vmcnt(" #n ")" ::: "memory")
; #define PG8_WAIT_L(n) asm volatile("s_waitcnt lgkmcnt(" #n ")" ::: "memory")
; #define PG8_BAR __builtin_amdgcn_s_barrier()
; #define PG8_SCHED __builtin_amdgcn_sched_barrier(0)
; template <class Epi>
; __device__ __forceinline__ void gemm_phase(LAS unsigned char* lds, const Gemm g, const StaticOrder& S, const Epi& E) {
;     ...
;             PG8_LDB(B0, 0, 0); PG8_SCHED; PG8_LDA(At, 0, 0); PG8_STAGE(PG8_SA(1, 1), a1 + hstep, voffA);
;             PG8_WAIT_L(8); PG8_BAR; PG8_WAIT_L(0); PG8_MMA(0, 0, At, B0); PG8_BAR; PG8_SCHED;
;             PG8_LDB(B1, 0, 1); PG8_STAGE(PG8_SB(0, 0), b2, voffB);
;             PG8_BAR; PG8_WAIT_L(0); PG8_MMA(0, 1, At, B1); PG8_BAR;
;             PG8_LDA(At, 0, 1); PG8_STAGE(PG8_SA(0, 0), a2, voffA);
;             PG8_BAR; PG8_WAIT_L(0); PG8_MMA(1, 0, At, B0); PG8_BAR; PG8_SCHED;
;             PG8_STAGE(PG8_SB(0, 1), b2 + hstep, voffB);
;             PG8_WAIT_V(6); PG8_BAR; PG8_MMA(1, 1, At, B1); PG8_BAR;
;             PG8_LDB(B0, 1, 0); PG8_SCHED; PG8_LDA(At, 1, 0); PG8_STAGE(PG8_SA(0, 1), a2 + hstep, voffA);
;             PG8_WAIT_L(8); PG8_BAR; PG8_WAIT_L(0); PG8_MMA(0, 0, At, B0); PG8_BAR; PG8_SCHED;
.Lprio_164:
.LBB0_164:
	s_add_u32 s48, s46, s60
	s_addc_u32 s49, s47, s61
	s_add_u32 s48, s48, 0x100
	s_addc_u32 s49, s49, 0
	s_add_u32 s56, s70, s60
	s_addc_u32 s57, s71, s61
	s_add_i32 s58, 0, 0x10000
	v_add_u32_e32 v140, s58, v143
	ds_read_b128 v[148:151], v140
	ds_read_b128 v[152:155], v140 offset:1024
	ds_read_b128 v[156:159], v140 offset:2048
	ds_read_b128 v[172:175], v140 offset:3072
	s_cmpk_eq_i32 s60, 0x1500
	s_cselect_b32 s51, s37, s49
	s_cselect_b32 s50, s36, s48
	s_cselect_b32 s49, s45, s57
	s_cselect_b32 s48, s44, s56
	v_lshl_add_u64 v[140:141], v[136:137], 0, s[60:61]
	s_add_i32 m0, s53, 0xc000
	ds_read_b128 v[178:181], v147
	ds_read_b128 v[182:185], v147 offset:1024
	ds_read_b128 v[186:189], v147 offset:2048
	ds_read_b128 v[190:193], v147 offset:3072
	ds_read_b128 v[194:197], v147 offset:4096
	ds_read_b128 v[198:201], v147 offset:5120
	ds_read_b128 v[202:205], v147 offset:6144
	ds_read_b128 v[206:209], v147 offset:7168
	global_load_lds_dwordx4 v[140:141], off
	v_lshl_add_u64 v[140:141], v[138:139], 0, s[60:61]
	s_add_i32 m0, s53, 0xe000
	s_nop 0
	global_load_lds_dwordx4 v[140:141], off
	s_waitcnt lgkmcnt(8)
	s_barrier
	s_waitcnt lgkmcnt(0)
	s_waitcnt lgkmcnt(0)
	s_nop 0
	v_mfma_f32_16x16x32_bf16 v[126:129], v[148:151], v[178:181], v[126:129]
	v_mfma_f32_16x16x32_bf16 v[122:125], v[156:159], v[178:181], v[122:125]
	v_mfma_f32_16x16x32_bf16 v[110:113], v[148:151], v[186:189], v[110:113]
	v_mfma_f32_16x16x32_bf16 v[106:109], v[156:159], v[186:189], v[106:109]
	v_mfma_f32_16x16x32_bf16 v[94:97], v[148:151], v[194:197], v[94:97]
	v_mfma_f32_16x16x32_bf16 v[90:93], v[156:159], v[194:197], v[90:93]
	v_mfma_f32_16x16x32_bf16 v[78:81], v[148:151], v[202:205], v[78:81]
	v_mfma_f32_16x16x32_bf16 v[74:77], v[156:159], v[202:205], v[74:77]
	v_mfma_f32_16x16x32_bf16 v[126:129], v[152:155], v[182:185], v[126:129]
	v_mfma_f32_16x16x32_bf16 v[122:125], v[172:175], v[182:185], v[122:125]
	v_mfma_f32_16x16x32_bf16 v[110:113], v[152:155], v[190:193], v[110:113]
	v_mfma_f32_16x16x32_bf16 v[106:109], v[172:175], v[190:193], v[106:109]
	v_mfma_f32_16x16x32_bf16 v[94:97], v[152:155], v[198:201], v[94:97]
	v_mfma_f32_16x16x32_bf16 v[90:93], v[172:175], v[198:201], v[90:93]
	v_mfma_f32_16x16x32_bf16 v[78:81], v[152:155], v[206:209], v[78:81]
	v_mfma_f32_16x16x32_bf16 v[74:77], v[172:175], v[206:209], v[74:77]
	s_barrier
	s_add_i32 s56, 0, 0x14000
	v_add_u32_e32 v140, s56, v143
	s_add_i32 s57, s58, s52
	ds_read_b128 v[210:213], v140
	ds_read_b128 v[214:217], v140 offset:1024
	ds_read_b128 v[218:221], v140 offset:2048
	ds_read_b128 v[246:249], v140 offset:3072
	v_lshl_add_u64 v[140:141], s[48:49], 0, v[0:1]
	s_mov_b32 m0, s57
	v_lshl_add_u64 v[160:161], s[48:49], 0, v[130:131]
	global_load_lds_dwordx4 v[140:141], off
	s_add_i32 m0, s57, 0x2000
	s_nop 0
	global_load_lds_dwordx4 v[160:161], off
	s_barrier
	s_waitcnt lgkmcnt(0)
	s_waitcnt lgkmcnt(0)
	v_mfma_f32_16x16x32_bf16 v[118:121], v[210:213], v[178:181], v[118:121]
	v_mfma_f32_16x16x32_bf16 v[114:117], v[218:221], v[178:181], v[114:117]
	v_mfma_f32_16x16x32_bf16 v[102:105], v[210:213], v[186:189], v[102:105]
	v_mfma_f32_16x16x32_bf16 v[98:101], v[218:221], v[186:189], v[98:101]
	v_mfma_f32_16x16x32_bf16 v[86:89], v[210:213], v[194:197], v[86:89]
	v_mfma_f32_16x16x32_bf16 v[82:85], v[218:221], v[194:197], v[82:85]
	v_mfma_f32_16x16x32_bf16 v[70:73], v[210:213], v[202:205], v[70:73]
	v_mfma_f32_16x16x32_bf16 v[66:69], v[218:221], v[202:205], v[66:69]
	v_mfma_f32_16x16x32_bf16 v[118:121], v[214:217], v[182:185], v[118:121]
	v_mfma_f32_16x16x32_bf16 v[114:117], v[246:249], v[182:185], v[114:117]
	v_mfma_f32_16x16x32_bf16 v[102:105], v[214:217], v[190:193], v[102:105]
	v_mfma_f32_16x16x32_bf16 v[98:101], v[246:249], v[190:193], v[98:101]
	v_mfma_f32_16x16x32_bf16 v[86:89], v[214:217], v[198:201], v[86:89]
	v_mfma_f32_16x16x32_bf16 v[82:85], v[246:249], v[198:201], v[82:85]
	v_mfma_f32_16x16x32_bf16 v[70:73], v[214:217], v[206:209], v[70:73]
	v_mfma_f32_16x16x32_bf16 v[66:69], v[246:249], v[206:209], v[66:69]
	s_mov_b32 m0, s53
	v_lshl_add_u64 v[222:223], s[50:51], 0, v[0:1]
	s_barrier
	ds_read_b128 v[178:181], v147 offset:16384
	ds_read_b128 v[182:185], v147 offset:17408
	ds_read_b128 v[186:189], v147 offset:18432
	ds_read_b128 v[190:193], v147 offset:19456
	ds_read_b128 v[194:197], v147 offset:20480
	ds_read_b128 v[198:201], v147 offset:21504
	ds_read_b128 v[202:205], v147 offset:22528
	ds_read_b128 v[206:209], v147 offset:23552
	global_load_lds_dwordx4 v[222:223], off
	v_lshl_add_u64 v[236:237], s[50:51], 0, v[130:131]
	s_mov_b32 m0, s54
	s_nop 0
	global_load_lds_dwordx4 v[236:237], off
	s_barrier
	s_waitcnt lgkmcnt(0)
	s_waitcnt lgkmcnt(0)
	s_nop 0
	v_mfma_f32_16x16x32_bf16 v[62:65], v[148:151], v[178:181], v[62:65]
	v_mfma_f32_16x16x32_bf16 v[58:61], v[156:159], v[178:181], v[58:61]
	v_mfma_f32_16x16x32_bf16 v[46:49], v[148:151], v[186:189], v[46:49]
	v_mfma_f32_16x16x32_bf16 v[42:45], v[156:159], v[186:189], v[42:45]
	v_mfma_f32_16x16x32_bf16 v[30:33], v[148:151], v[194:197], v[30:33]
	v_mfma_f32_16x16x32_bf16 v[26:29], v[156:159], v[194:197], v[26:29]
	v_mfma_f32_16x16x32_bf16 v[14:17], v[148:151], v[202:205], v[14:17]
	v_mfma_f32_16x16x32_bf16 v[10:13], v[156:159], v[202:205], v[10:13]
	v_mfma_f32_16x16x32_bf16 v[62:65], v[152:155], v[182:185], v[62:65]
	v_mfma_f32_16x16x32_bf16 v[58:61], v[172:175], v[182:185], v[58:61]
	v_mfma_f32_16x16x32_bf16 v[46:49], v[152:155], v[190:193], v[46:49]
	v_mfma_f32_16x16x32_bf16 v[42:45], v[172:175], v[190:193], v[42:45]
	v_mfma_f32_16x16x32_bf16 v[30:33], v[152:155], v[198:201], v[30:33]
	v_mfma_f32_16x16x32_bf16 v[26:29], v[172:175], v[198:201], v[26:29]
	v_mfma_f32_16x16x32_bf16 v[14:17], v[152:155], v[206:209], v[14:17]
	v_mfma_f32_16x16x32_bf16 v[10:13], v[172:175], v[206:209], v[10:13]
	s_barrier
; #define PG8_STAGE(bufoff, gbase, voff) do { _Pragma("unroll") for (int _i = 0; _i < 2; ++_i) \
;         __builtin_amdgcn_global_load_lds((const unsigned*)((const char*)(gbase) + (voff)[_i]), (LAS unsigned*)(lds + (bufoff) + ldsw + _i * 8192), 16, 0, 0); } while (0)
; #define PG8_LDA(dst, b, h) do { _Pragma("unroll") for (int m = 0; m < 4; ++m) _Pragma("unroll") for (int k = 0; k < 2; ++k) dst[m][k] = *(const LAS bf16x8*)(lds + PG8_SA(b, h) + aoff + m * 2048 + k * 1024); } while (0)
; #define PG8_LDB(dst, b, h) do { _Pragma("unroll") for (int n = 0; n < 2; ++n) _Pragma("unroll") for (int k = 0; k < 2; ++k) dst[n][k] = *(const LAS bf16x8*)(lds + PG8_SB(b, h) + boff + n * 2048 + k * 1024); } while (0)
; #define PG8_MMA(ai, bj, At, Bt) do { __builtin_amdgcn_s_setprio(1); _Pragma("unroll") for (int m = 0; m < 4; ++m) _Pragma("unroll") for (int n = 0; n < 2; ++n) _Pragma("unroll") for (int k = 0; k < 2; ++k) \
;         acc[ai][bj][m][n] = __builtin_amdgcn_mfma_f32_16x16x32_bf16(Bt[n][k], At[m][k], acc[ai][bj][m][n], 0, 0, 0); __builtin_amdgcn_s_setprio(0); } while (0)
; #define PG8_WAIT_V(n) asm volatile("s_waitcnt vmcnt(" #n ")" ::: "memory")
; #define PG8_WAIT_L(n) asm volatile("s_waitcnt lgkmcnt(" #n ")" ::: "memory")
; #define PG8_BAR __builtin_amdgcn_s_barrier()
; #define PG8_SCHED __builtin_amdgcn_sched_barrier(0)
; template <class Epi>
; __device__ __forceinline__ void gemm_phase(LAS unsigned char* lds, const Gemm g, const StaticOrder& S, const Epi& E) {
;     ...
;             PG8_STAGE(PG8_SB(0, 1), b2 + hstep, voffB);
;             PG8_WAIT_V(6); PG8_BAR; PG8_MMA(1, 1, At, B1); PG8_BAR;
;             PG8_LDB(B0, 1, 0); PG8_SCHED; PG8_LDA(At, 1, 0); PG8_STAGE(PG8_SA(0, 1), a2 + hstep, voffA);
;             PG8_WAIT_L(8); PG8_BAR; PG8_WAIT_L(0); PG8_MMA(0, 0, At, B0); PG8_BAR; PG8_SCHED;
;             PG8_LDB(B1, 1, 1); PG8_STAGE(PG8_SB(1, 0), b3, voffB);
;             PG8_BAR; PG8_WAIT_L(0); PG8_MMA(0, 1, At, B1); PG8_BAR;
;             PG8_LDA(At, 1, 1); PG8_STAGE(PG8_SA(1, 0), a3, voffA);
;             PG8_BAR; PG8_WAIT_L(0); PG8_MMA(1, 0, At, B0); PG8_BAR; PG8_SCHED;
	s_add_u32 s58, s48, 0xb0000
	s_addc_u32 s59, s49, 0
	s_add_i32 s56, s56, s52
	v_lshl_add_u64 v[148:149], s[58:59], 0, v[0:1]
	s_mov_b32 m0, s56
	s_nop 0
	global_load_lds_dwordx4 v[148:149], off
	v_lshl_add_u64 v[148:149], s[58:59], 0, v[130:131]
	s_add_i32 m0, s56, 0x2000
	s_nop 0
	global_load_lds_dwordx4 v[148:149], off
	s_waitcnt vmcnt(6)
	s_barrier
	v_mfma_f32_16x16x32_bf16 v[54:57], v[210:213], v[178:181], v[54:57]
	v_mfma_f32_16x16x32_bf16 v[50:53], v[218:221], v[178:181], v[50:53]
	v_mfma_f32_16x16x32_bf16 v[38:41], v[210:213], v[186:189], v[38:41]
	v_mfma_f32_16x16x32_bf16 v[34:37], v[218:221], v[186:189], v[34:37]
	v_mfma_f32_16x16x32_bf16 v[22:25], v[210:213], v[194:197], v[22:25]
	v_mfma_f32_16x16x32_bf16 v[18:21], v[218:221], v[194:197], v[18:21]
	v_mfma_f32_16x16x32_bf16 v[6:9], v[210:213], v[202:205], v[6:9]
	v_mfma_f32_16x16x32_bf16 v[2:5], v[218:221], v[202:205], v[2:5]
	v_mfma_f32_16x16x32_bf16 v[54:57], v[214:217], v[182:185], v[54:57]
	v_mfma_f32_16x16x32_bf16 v[50:53], v[246:249], v[182:185], v[50:53]
	v_mfma_f32_16x16x32_bf16 v[38:41], v[214:217], v[190:193], v[38:41]
	v_mfma_f32_16x16x32_bf16 v[34:37], v[246:249], v[190:193], v[34:37]
	v_mfma_f32_16x16x32_bf16 v[22:25], v[214:217], v[198:201], v[22:25]
	v_mfma_f32_16x16x32_bf16 v[18:21], v[246:249], v[198:201], v[18:21]
	v_mfma_f32_16x16x32_bf16 v[6:9], v[214:217], v[206:209], v[6:9]
	v_mfma_f32_16x16x32_bf16 v[2:5], v[246:249], v[206:209], v[2:5]
	s_add_i32 s56, 0, 0x18000
	v_add_u32_e32 v172, s56, v143
	s_barrier
	ds_read_b128 v[148:151], v172
	ds_read_b128 v[152:155], v172 offset:1024
	ds_read_b128 v[156:159], v172 offset:2048
	ds_read_b128 v[172:175], v172 offset:3072
	s_add_u32 s50, s50, 0xb0000
	s_addc_u32 s51, s51, 0
	s_mov_b32 m0, s55
	v_lshl_add_u64 v[210:211], s[50:51], 0, v[0:1]
	ds_read_b128 v[178:181], v147 offset:32768
	ds_read_b128 v[182:185], v147 offset:33792
	ds_read_b128 v[186:189], v147 offset:34816
	ds_read_b128 v[190:193], v147 offset:35840
	ds_read_b128 v[194:197], v147 offset:36864
	ds_read_b128 v[198:201], v147 offset:37888
	ds_read_b128 v[202:205], v147 offset:38912
	ds_read_b128 v[206:209], v147 offset:39936
	global_load_lds_dwordx4 v[210:211], off
	v_lshl_add_u64 v[210:211], s[50:51], 0, v[130:131]
	s_mov_b32 m0, s63
	s_nop 0
	global_load_lds_dwordx4 v[210:211], off
	s_waitcnt lgkmcnt(8)
	s_barrier
	s_waitcnt lgkmcnt(0)
	s_waitcnt lgkmcnt(0)
	v_mfma_f32_16x16x32_bf16 v[126:129], v[148:151], v[178:181], v[126:129]
	v_mfma_f32_16x16x32_bf16 v[122:125], v[156:159], v[178:181], v[122:125]
	v_mfma_f32_16x16x32_bf16 v[110:113], v[148:151], v[186:189], v[110:113]
	v_mfma_f32_16x16x32_bf16 v[106:109], v[156:159], v[186:189], v[106:109]
	v_mfma_f32_16x16x32_bf16 v[94:97], v[148:151], v[194:197], v[94:97]
	v_mfma_f32_16x16x32_bf16 v[90:93], v[156:159], v[194:197], v[90:93]
	v_mfma_f32_16x16x32_bf16 v[78:81], v[148:151], v[202:205], v[78:81]
	v_mfma_f32_16x16x32_bf16 v[74:77], v[156:159], v[202:205], v[74:77]
	v_mfma_f32_16x16x32_bf16 v[126:129], v[152:155], v[182:185], v[126:129]
	v_mfma_f32_16x16x32_bf16 v[122:125], v[172:175], v[182:185], v[122:125]
	v_mfma_f32_16x16x32_bf16 v[110:113], v[152:155], v[190:193], v[110:113]
	v_mfma_f32_16x16x32_bf16 v[106:109], v[172:175], v[190:193], v[106:109]
	v_mfma_f32_16x16x32_bf16 v[94:97], v[152:155], v[198:201], v[94:97]
	v_mfma_f32_16x16x32_bf16 v[90:93], v[172:175], v[198:201], v[90:93]
	v_mfma_f32_16x16x32_bf16 v[78:81], v[152:155], v[206:209], v[78:81]
	v_mfma_f32_16x16x32_bf16 v[74:77], v[172:175], v[206:209], v[74:77]
	s_barrier
	s_add_i32 s50, 0, 0x1c000
	s_add_i32 s51, s56, s52
	v_add_u32_e32 v177, s50, v143
	v_lshl_add_u64 v[140:141], v[140:141], 0, s[28:29]
	s_mov_b32 m0, s51
	ds_read_b128 v[210:213], v177
	ds_read_b128 v[214:217], v177 offset:1024
	ds_read_b128 v[218:221], v177 offset:2048
	ds_read_b128 v[246:249], v177 offset:3072
	global_load_lds_dwordx4 v[140:141], off
	v_lshl_add_u64 v[140:141], v[160:161], 0, s[28:29]
	s_add_i32 m0, s51, 0x2000
	s_nop 0
	global_load_lds_dwordx4 v[140:141], off
	s_barrier
	s_waitcnt lgkmcnt(0)
	s_waitcnt lgkmcnt(0)
	v_mfma_f32_16x16x32_bf16 v[118:121], v[210:213], v[178:181], v[118:121]
	v_mfma_f32_16x16x32_bf16 v[114:117], v[218:221], v[178:181], v[114:117]
	v_mfma_f32_16x16x32_bf16 v[102:105], v[210:213], v[186:189], v[102:105]
	v_mfma_f32_16x16x32_bf16 v[98:101], v[218:221], v[186:189], v[98:101]
	v_mfma_f32_16x16x32_bf16 v[86:89], v[210:213], v[194:197], v[86:89]
	v_mfma_f32_16x16x32_bf16 v[82:85], v[218:221], v[194:197], v[82:85]
	v_mfma_f32_16x16x32_bf16 v[70:73], v[210:213], v[202:205], v[70:73]
	v_mfma_f32_16x16x32_bf16 v[66:69], v[218:221], v[202:205], v[66:69]
	v_mfma_f32_16x16x32_bf16 v[118:121], v[214:217], v[182:185], v[118:121]
	v_mfma_f32_16x16x32_bf16 v[114:117], v[246:249], v[182:185], v[114:117]
	v_mfma_f32_16x16x32_bf16 v[102:105], v[214:217], v[190:193], v[102:105]
	v_mfma_f32_16x16x32_bf16 v[98:101], v[246:249], v[190:193], v[98:101]
	v_mfma_f32_16x16x32_bf16 v[86:89], v[214:217], v[198:201], v[86:89]
	v_mfma_f32_16x16x32_bf16 v[82:85], v[246:249], v[198:201], v[82:85]
	v_mfma_f32_16x16x32_bf16 v[70:73], v[214:217], v[206:209], v[70:73]
	v_mfma_f32_16x16x32_bf16 v[66:69], v[246:249], v[206:209], v[66:69]
	s_mov_b32 m0, s64
	v_lshl_add_u64 v[140:141], v[222:223], 0, s[28:29]
	s_barrier
	ds_read_b128 v[178:181], v147 offset:49152
	ds_read_b128 v[182:185], v147 offset:50176
	ds_read_b128 v[186:189], v147 offset:51200
	ds_read_b128 v[190:193], v147 offset:52224
	ds_read_b128 v[194:197], v147 offset:53248
	ds_read_b128 v[198:201], v147 offset:54272
	ds_read_b128 v[202:205], v147 offset:55296
	ds_read_b128 v[206:209], v147 offset:56320
	global_load_lds_dwordx4 v[140:141], off
	v_lshl_add_u64 v[140:141], v[236:237], 0, s[28:29]
	s_mov_b32 m0, s65
	s_nop 0
	global_load_lds_dwordx4 v[140:141], off
	s_barrier
; __device__ __forceinline__ u64 ss_fix(float ss) { return (u64)(ss * 1048576.f + 0.5f); }
; __device__ __forceinline__ unsigned pk2(float lo, float hi) { unsigned r; asm volatile("v_cvt_pk_bf16_f32 %0, %1, %2" : "=v"(r) : "v"(lo), "v"(hi)); return r; }
; __device__ __forceinline__ float shfl_xor_(float v, int o, int lane) { return shfl_idx(v, lane ^ o); }
; #define PG8_STAGE(bufoff, gbase, voff) do { _Pragma("unroll") for (int _i = 0; _i < 2; ++_i) \
;         __builtin_amdgcn_global_load_lds((const unsigned*)((const char*)(gbase) + (voff)[_i]), (LAS unsigned*)(lds + (bufoff) + ldsw + _i * 8192), 16, 0, 0); } while (0)
; #define PG8_WAIT_V(n) asm volatile("s_waitcnt vmcnt(" #n ")" ::: "memory")
; #define PG8_WAIT_L(n) asm volatile("s_waitcnt lgkmcnt(" #n ")" ::: "memory")
; #define PG8_BAR __builtin_amdgcn_s_barrier()
; #define PG8_SCHED __builtin_amdgcn_sched_barrier(0)
; template <class Epi>
; __device__ __forceinline__ void gemm_phase(LAS unsigned char* lds, const Gemm g, const StaticOrder& S, const Epi& E) {
;     ...
;             PG8_BAR; PG8_WAIT_L(0); PG8_MMA(1, 0, At, B0); PG8_BAR; PG8_SCHED;
;             PG8_STAGE(PG8_SB(1, 1), b3 + hstep, voffB);
;             PG8_WAIT_V(6); PG8_BAR; PG8_MMA(1, 1, At, B1); PG8_BAR;
;     __device__ __forceinline__ void operator()(const f32x4 (&acc)[2][2][4][2], const Unit& u, int wr, int wc, int fr, int fq) const {
;         const int row0 = u.pm * BM + wr * 64 + fr, col0 = u.pn * BM + wc * 32 + 4 * fq, lane = fr | (fq << 4);
; #pragma unroll
;         for (int ai = 0; ai < 2; ++ai)
; #pragma unroll
;             for (int m = 0; m < 4; ++m) { const int row = row0 + ai * HALF + m * 16; bf16_t* xbp = xb + (size_t)row * ldc + col0;
;                 float ss = 0.f;
; #pragma unroll
;                 for (int bj = 0; bj < 2; ++bj)
; #pragma unroll
;                     for (int n = 0; n < 2; ++n) { u32x2* pp = (u32x2*)(xbp + bj * HALF + n * 16); float o[4]; unpack4(*pp, o);
;                         u32x2 w; w.x = pk2(o[0] + acc[ai][bj][m][n][0], o[1] + acc[ai][bj][m][n][1]); w.y = pk2(o[2] + acc[ai][bj][m][n][2], o[3] + acc[ai][bj][m][n][3]); *pp = w;
;                         unpack4(w, o); ss += o[0] * o[0] + o[1] * o[1] + o[2] * o[2] + o[3] * o[3]; }
;                 ss += shfl_xor_(ss, 16, lane); ss += shfl_xor_(ss, 32, lane);
;                 if (fq == 0) atomicAdd(rss + row, ss_fix(ss)); }
	s_waitcnt lgkmcnt(0)
	s_waitcnt lgkmcnt(0)
	s_nop 0
	v_mfma_f32_16x16x32_bf16 v[62:65], v[148:151], v[178:181], v[62:65]
	v_mfma_f32_16x16x32_bf16 v[58:61], v[156:159], v[178:181], v[58:61]
	v_mfma_f32_16x16x32_bf16 v[46:49], v[148:151], v[186:189], v[46:49]
	v_mfma_f32_16x16x32_bf16 v[42:45], v[156:159], v[186:189], v[42:45]
	v_mfma_f32_16x16x32_bf16 v[30:33], v[148:151], v[194:197], v[30:33]
	v_mfma_f32_16x16x32_bf16 v[26:29], v[156:159], v[194:197], v[26:29]
	v_mfma_f32_16x16x32_bf16 v[14:17], v[148:151], v[202:205], v[14:17]
	v_mfma_f32_16x16x32_bf16 v[10:13], v[156:159], v[202:205], v[10:13]
	v_mfma_f32_16x16x32_bf16 v[62:65], v[152:155], v[182:185], v[62:65]
	v_mfma_f32_16x16x32_bf16 v[58:61], v[172:175], v[182:185], v[58:61]
	v_mfma_f32_16x16x32_bf16 v[46:49], v[152:155], v[190:193], v[46:49]
	v_mfma_f32_16x16x32_bf16 v[42:45], v[172:175], v[190:193], v[42:45]
	v_mfma_f32_16x16x32_bf16 v[30:33], v[152:155], v[198:201], v[30:33]
	v_mfma_f32_16x16x32_bf16 v[26:29], v[172:175], v[198:201], v[26:29]
	v_mfma_f32_16x16x32_bf16 v[14:17], v[152:155], v[206:209], v[14:17]
	v_mfma_f32_16x16x32_bf16 v[10:13], v[172:175], v[206:209], v[10:13]
	s_barrier
	s_add_u32 s48, s48, 0xb0080
	s_addc_u32 s49, s49, 0
	s_add_i32 s50, s50, s52
	v_lshl_add_u64 v[140:141], s[48:49], 0, v[0:1]
	s_mov_b32 m0, s50
	s_nop 0
	global_load_lds_dwordx4 v[140:141], off
	v_lshl_add_u64 v[140:141], s[48:49], 0, v[130:131]
	s_add_i32 m0, s50, 0x2000
	s_nop 0
	global_load_lds_dwordx4 v[140:141], off
	s_waitcnt vmcnt(6)
	s_barrier
	v_mfma_f32_16x16x32_bf16 v[54:57], v[210:213], v[178:181], v[54:57]
	v_mfma_f32_16x16x32_bf16 v[50:53], v[218:221], v[178:181], v[50:53]
	v_mfma_f32_16x16x32_bf16 v[38:41], v[210:213], v[186:189], v[38:41]
	v_mfma_f32_16x16x32_bf16 v[34:37], v[218:221], v[186:189], v[34:37]
	v_mfma_f32_16x16x32_bf16 v[22:25], v[210:213], v[194:197], v[22:25]
	v_mfma_f32_16x16x32_bf16 v[18:21], v[218:221], v[194:197], v[18:21]
	v_mfma_f32_16x16x32_bf16 v[6:9], v[210:213], v[202:205], v[6:9]
	v_mfma_f32_16x16x32_bf16 v[2:5], v[218:221], v[202:205], v[2:5]
	v_mfma_f32_16x16x32_bf16 v[54:57], v[214:217], v[182:185], v[54:57]
	v_mfma_f32_16x16x32_bf16 v[50:53], v[246:249], v[182:185], v[50:53]
	v_mfma_f32_16x16x32_bf16 v[38:41], v[214:217], v[190:193], v[38:41]
	v_mfma_f32_16x16x32_bf16 v[34:37], v[246:249], v[190:193], v[34:37]
	v_mfma_f32_16x16x32_bf16 v[22:25], v[214:217], v[198:201], v[22:25]
	v_mfma_f32_16x16x32_bf16 v[18:21], v[246:249], v[198:201], v[18:21]
	v_mfma_f32_16x16x32_bf16 v[6:9], v[214:217], v[206:209], v[6:9]
	v_mfma_f32_16x16x32_bf16 v[2:5], v[246:249], v[206:209], v[2:5]
	s_add_i32 s93, s93, 2
	s_add_u32 s60, s60, 0x100
	s_addc_u32 s61, s61, 0
	s_cmp_gt_u32 s93, 41
	s_barrier
	s_cbranch_scc0 .LBB0_164
	s_setprio 0
	s_add_u32 s48, s70, 0xffffff00
	s_addc_u32 s49, s71, -1
	s_and_b64 vcc, exec, s[0:1]
	s_movk_i32 s93, 0x1000
	s_cbranch_vccz .LBB0_183
	v_lshl_add_u32 v140, s68, 8, v142
	v_ashrrev_i32_e32 v141, 31, v140
	v_readlane_b32 s0, v252, 51
	v_lshl_or_b32 v138, s67, 8, v144
	v_lshlrev_b64 v[136:137], 11, v[140:141]
	v_readlane_b32 s1, v252, 52
	v_ashrrev_i32_e32 v139, 31, v138
	s_nop 0
	v_lshl_add_u64 v[136:137], s[0:1], 0, v[136:137]
	v_lshl_add_u64 v[136:137], v[138:139], 1, v[136:137]
	global_load_dwordx2 v[148:149], v[136:137], off
	s_waitcnt vmcnt(0)
	v_lshlrev_b32_e32 v150, 16, v148
	v_and_b32_e32 v148, 0xffff0000, v148
	v_lshlrev_b32_e32 v151, 16, v149
	v_and_b32_e32 v149, 0xffff0000, v149
	v_add_f32_e32 v126, v126, v150
	v_add_f32_e32 v127, v127, v148
	v_add_f32_e32 v128, v128, v151
	v_add_f32_e32 v129, v129, v149
	v_cvt_pk_bf16_f32 v126, v126, v127
	v_cvt_pk_bf16_f32 v127, v128, v129
	global_load_dwordx2 v[128:129], v[136:137], off offset:32
	s_waitcnt vmcnt(0)
	v_lshlrev_b32_e32 v148, 16, v128
	v_and_b32_e32 v128, 0xffff0000, v128
	v_lshlrev_b32_e32 v149, 16, v129
	v_and_b32_e32 v129, 0xffff0000, v129
	v_add_f32_e32 v122, v122, v148
	v_add_f32_e32 v123, v123, v128
	v_add_f32_e32 v124, v124, v149
	v_add_f32_e32 v125, v125, v129
	global_store_dwordx2 v[136:137], v[126:127], off
	v_cvt_pk_bf16_f32 v122, v122, v123
	v_cvt_pk_bf16_f32 v123, v124, v125
	global_load_dwordx2 v[124:125], v[136:137], off offset:256
	s_waitcnt vmcnt(0)
	v_lshlrev_b32_e32 v128, 16, v124
	v_and_b32_e32 v124, 0xffff0000, v124
	v_lshlrev_b32_e32 v129, 16, v125
	v_and_b32_e32 v125, 0xffff0000, v125
	v_add_f32_e32 v118, v118, v128
	v_add_f32_e32 v119, v119, v124
	v_add_f32_e32 v120, v120, v129
	v_add_f32_e32 v121, v121, v125
	global_store_dwordx2 v[136:137], v[122:123], off offset:32
	v_cvt_pk_bf16_f32 v118, v118, v119
	v_cvt_pk_bf16_f32 v119, v120, v121
	global_load_dwordx2 v[120:121], v[136:137], off offset:288
	v_and_b32_e32 v125, 0xffff0000, v126
	v_lshlrev_b32_e32 v124, 16, v126
	v_mul_f32_e32 v125, v125, v125
	v_fmac_f32_e32 v125, v124, v124
	v_lshlrev_b32_e32 v124, 16, v122
	v_and_b32_e32 v122, 0xffff0000, v122
	v_lshlrev_b32_e32 v126, 16, v127
	v_mul_f32_e32 v122, v122, v122
	v_fmac_f32_e32 v125, v126, v126
	v_lshlrev_b32_e32 v126, 16, v123
	v_fmac_f32_e32 v122, v124, v124
	v_and_b32_e32 v123, 0xffff0000, v123
	v_fmac_f32_e32 v122, v126, v126
	v_fmac_f32_e32 v122, v123, v123
	global_store_dwordx2 v[136:137], v[118:119], off offset:256
	v_lshlrev_b32_e32 v123, 16, v118
	v_and_b32_e32 v118, 0xffff0000, v118
	v_mul_f32_e32 v118, v118, v118
	v_and_b32_e32 v127, 0xffff0000, v127
	v_lshlrev_b32_e32 v124, 16, v119
	v_fmac_f32_e32 v118, v123, v123
	v_fmac_f32_e32 v125, v127, v127
	v_and_b32_e32 v119, 0xffff0000, v119
	v_fmac_f32_e32 v118, v124, v124
	v_add_f32_e32 v122, v125, v122
	v_fmac_f32_e32 v118, v119, v119
	v_add_f32_e32 v118, v122, v118
	s_waitcnt vmcnt(0)
	v_lshlrev_b32_e32 v119, 16, v120
	v_and_b32_e32 v120, 0xffff0000, v120
	v_lshlrev_b32_e32 v122, 16, v121
	v_and_b32_e32 v121, 0xffff0000, v121
	v_add_f32_e32 v114, v114, v119
	v_add_f32_e32 v115, v115, v120
	v_add_f32_e32 v117, v117, v121
	v_add_f32_e32 v116, v116, v122
	v_cvt_pk_bf16_f32 v114, v114, v115
	v_cvt_pk_bf16_f32 v115, v116, v117
	global_store_dwordx2 v[136:137], v[114:115], off offset:288
	v_and_b32_e32 v117, 0xffff0000, v114
	v_lshlrev_b32_e32 v116, 16, v114
	v_mul_f32_e32 v117, v117, v117
	v_lshlrev_b32_e32 v119, 16, v115
	v_fmac_f32_e32 v117, v116, v116
	v_and_b32_e32 v120, 0xffff0000, v115
	v_fmac_f32_e32 v117, v119, v119
	v_fmac_f32_e32 v117, v120, v120
	v_add_f32_e32 v116, v118, v117
	ds_bpermute_b32 v117, v145, v116
	v_lshl_add_u64 v[114:115], v[140:141], 3, s[72:73]
	s_waitcnt lgkmcnt(0)
	v_add_f32_e32 v116, v116, v117
	ds_bpermute_b32 v117, v146, v116
	s_and_saveexec_b64 s[0:1], s[40:41]
	v_readlane_b32 s84, v254, 44
	v_readlane_b32 s85, v254, 45
	s_cbranch_execz .LBB0_168
	s_waitcnt lgkmcnt(0)
	v_add_f32_e32 v116, v116, v117
	s_mov_b32 s46, 0x49800000
	v_fma_f32 v116, v116, s46, 0.5
	v_trunc_f32_e32 v116, v116
	v_mul_f32_e32 v117, 0x2f800000, v116
	v_floor_f32_e32 v117, v117
	v_fmac_f32_e32 v116, 0xcf800000, v117
	v_cvt_u32_f32_e32 v116, v116
	v_cvt_u32_f32_e32 v117, v117
	global_atomic_add_x2 v[114:115], v[116:117], off

; #define PG8_STAGE(bufoff, gbase, voff) do { _Pragma("unroll") for (int _i = 0; _i < 2; ++_i) \
;         __builtin_amdgcn_global_load_lds((const unsigned*)((const char*)(gbase) + (voff)[_i]), (LAS unsigned*)(lds + (bufoff) + ldsw + _i * 8192), 16, 0, 0); } while (0)
; #define PG8_LDA(dst, b, h) do { _Pragma("unroll") for (int m = 0; m < 4; ++m) _Pragma("unroll") for (int k = 0; k < 2; ++k) dst[m][k] = *(const LAS bf16x8*)(lds + PG8_SA(b, h) + aoff + m * 2048 + k * 1024); } while (0)
; #define PG8_LDB(dst, b, h) do { _Pragma("unroll") for (int n = 0; n < 2; ++n) _Pragma("unroll") for (int k = 0; k < 2; ++k) dst[n][k] = *(const LAS bf16x8*)(lds + PG8_SB(b, h) + boff + n * 2048 + k * 1024); } while (0)
; #define PG8_MMA(ai, bj, At, Bt) do { __builtin_amdgcn_s_setprio(1); _Pragma("unroll") for (int m = 0; m < 4; ++m) _Pragma("unroll") for (int n = 0; n < 2; ++n) _Pragma("unroll") for (int k = 0; k < 2; ++k) \
;         acc[ai][bj][m][n] = __builtin_amdgcn_mfma_f32_16x16x32_bf16(Bt[n][k], At[m][k], acc[ai][bj][m][n], 0, 0, 0); __builtin_amdgcn_s_setprio(0); } while (0)
; #define PG8_WAIT_V(n) asm volatile("s_waitcnt vmcnt(" #n ")" ::: "memory")
; #define PG8_WAIT_L(n) asm volatile("s_waitcnt lgkmcnt(" #n ")" ::: "memory")
; #define PG8_BAR __builtin_amdgcn_s_barrier()
; #define PG8_SCHED __builtin_amdgcn_sched_barrier(0)
; template <class Epi>
; __device__ __forceinline__ void gemm_phase(LAS unsigned char* lds, const Gemm g, const StaticOrder& S, const Epi& E) {
;     ...
;             PG8_LDB(B0, 0, 0); PG8_SCHED; PG8_LDA(At, 0, 0); PG8_STAGE(PG8_SA(1, 1), a1 + hstep, voffA);
;             PG8_WAIT_L(8); PG8_BAR; PG8_WAIT_L(0); PG8_MMA(0, 0, At, B0); PG8_BAR; PG8_SCHED;
;             PG8_LDB(B1, 0, 1); PG8_STAGE(PG8_SB(0, 0), b2, voffB);
;             PG8_BAR; PG8_WAIT_L(0); PG8_MMA(0, 1, At, B1); PG8_BAR;
;             PG8_LDA(At, 0, 1); PG8_STAGE(PG8_SA(0, 0), a2, voffA);
;             PG8_BAR; PG8_WAIT_L(0); PG8_MMA(1, 0, At, B0); PG8_BAR; PG8_SCHED;
;             PG8_STAGE(PG8_SB(0, 1), b2 + hstep, voffB);
;             PG8_WAIT_V(6); PG8_BAR; PG8_MMA(1, 1, At, B1); PG8_BAR;
.Lprio_211:
.LBB0_211:
	s_add_u32 s36, s0, 0xfffc0080
	s_addc_u32 s37, s1, -1
	s_add_i32 s58, 0, 0x10000
	v_add_u32_e32 v0, s58, v171
	ds_read_b128 v[42:45], v0
	ds_read_b128 v[46:49], v0 offset:1024
	ds_read_b128 v[50:53], v0 offset:2048
	ds_read_b128 v[54:57], v0 offset:3072
	s_cmp_eq_u32 s24, 12
	s_cselect_b32 s53, s65, s37
	s_cselect_b32 s52, s96, s36
	s_cselect_b32 s37, s63, vcc_hi
	s_cselect_b32 s36, s97, vcc_lo
	v_lshl_add_u64 v[202:203], s[0:1], 0, v[186:187]
	s_add_i32 m0, s30, 0xc000
	ds_read_b128 v[58:61], v242
	ds_read_b128 v[62:65], v242 offset:1024
	ds_read_b128 v[70:73], v242 offset:2048
	ds_read_b128 v[74:77], v242 offset:3072
	ds_read_b128 v[172:175], v242 offset:4096
	ds_read_b128 v[190:193], v242 offset:5120
	ds_read_b128 v[194:197], v242 offset:6144
	ds_read_b128 v[198:201], v242 offset:7168
	global_load_lds_dwordx4 v[202:203], off
	v_lshl_add_u64 v[202:203], s[0:1], 0, v[188:189]
	s_add_i32 m0, s30, 0xe000
	s_nop 0
	global_load_lds_dwordx4 v[202:203], off
	s_waitcnt lgkmcnt(8)
	s_barrier
	s_waitcnt lgkmcnt(0)
	s_waitcnt lgkmcnt(0)
	v_mfma_f32_16x16x32_bf16 v[158:161], v[42:45], v[58:61], v[158:161]
	v_mfma_f32_16x16x32_bf16 v[154:157], v[50:53], v[58:61], v[154:157]
	v_mfma_f32_16x16x32_bf16 v[142:145], v[42:45], v[70:73], v[142:145]
	v_mfma_f32_16x16x32_bf16 v[138:141], v[50:53], v[70:73], v[138:141]
	v_mfma_f32_16x16x32_bf16 v[126:129], v[42:45], v[172:175], v[126:129]
	v_mfma_f32_16x16x32_bf16 v[122:125], v[50:53], v[172:175], v[122:125]
	v_mfma_f32_16x16x32_bf16 v[110:113], v[42:45], v[194:197], v[110:113]
	v_mfma_f32_16x16x32_bf16 v[106:109], v[50:53], v[194:197], v[106:109]
	v_mfma_f32_16x16x32_bf16 v[158:161], v[46:49], v[62:65], v[158:161]
	v_mfma_f32_16x16x32_bf16 v[154:157], v[54:57], v[62:65], v[154:157]
	v_mfma_f32_16x16x32_bf16 v[142:145], v[46:49], v[74:77], v[142:145]
	v_mfma_f32_16x16x32_bf16 v[138:141], v[54:57], v[74:77], v[138:141]
	v_mfma_f32_16x16x32_bf16 v[126:129], v[46:49], v[190:193], v[126:129]
	v_mfma_f32_16x16x32_bf16 v[122:125], v[54:57], v[190:193], v[122:125]
	v_mfma_f32_16x16x32_bf16 v[110:113], v[46:49], v[198:201], v[110:113]
	v_mfma_f32_16x16x32_bf16 v[106:109], v[54:57], v[198:201], v[106:109]
	s_barrier
	s_add_i32 s56, 0, 0x14000
	s_add_i32 s57, s58, s26
	v_add_u32_e32 v0, s56, v171
	v_lshl_add_u64 v[222:223], s[36:37], 0, v[180:181]
	s_mov_b32 m0, s57
	ds_read_b128 v[202:205], v0
	ds_read_b128 v[206:209], v0 offset:1024
	ds_read_b128 v[210:213], v0 offset:2048
	ds_read_b128 v[214:217], v0 offset:3072
	global_load_lds_dwordx4 v[222:223], off
	v_lshl_add_u64 v[246:247], s[36:37], 0, v[176:177]
	s_add_i32 m0, s57, 0x2000
	s_nop 0
	global_load_lds_dwordx4 v[246:247], off
	s_barrier
	s_waitcnt lgkmcnt(0)
	s_waitcnt lgkmcnt(0)
	v_mfma_f32_16x16x32_bf16 v[150:153], v[202:205], v[58:61], v[150:153]
	v_mfma_f32_16x16x32_bf16 v[58:61], v[210:213], v[58:61], v[146:149]
	v_mfma_f32_16x16x32_bf16 v[150:153], v[206:209], v[62:65], v[150:153]
	v_mfma_f32_16x16x32_bf16 v[58:61], v[214:217], v[62:65], v[58:61]
	v_mfma_f32_16x16x32_bf16 v[62:65], v[202:205], v[70:73], v[130:133]
	v_mfma_f32_16x16x32_bf16 v[70:73], v[210:213], v[70:73], v[134:137]
	v_mfma_f32_16x16x32_bf16 v[62:65], v[206:209], v[74:77], v[62:65]
	v_mfma_f32_16x16x32_bf16 v[70:73], v[214:217], v[74:77], v[70:73]
	v_mfma_f32_16x16x32_bf16 v[74:77], v[202:205], v[172:175], v[114:117]
	v_mfma_f32_16x16x32_bf16 v[114:117], v[210:213], v[172:175], v[118:121]
	v_mfma_f32_16x16x32_bf16 v[98:101], v[202:205], v[194:197], v[98:101]
	v_mfma_f32_16x16x32_bf16 v[102:105], v[210:213], v[194:197], v[102:105]
	v_mfma_f32_16x16x32_bf16 v[118:121], v[214:217], v[190:193], v[114:117]
	v_mfma_f32_16x16x32_bf16 v[98:101], v[206:209], v[198:201], v[98:101]
	v_mfma_f32_16x16x32_bf16 v[102:105], v[214:217], v[198:201], v[102:105]
	v_mfma_f32_16x16x32_bf16 v[74:77], v[206:209], v[190:193], v[74:77]
	s_mov_b32 m0, s30
	v_lshl_add_u64 v[248:249], s[52:53], 0, v[182:183]
	s_barrier
	ds_read_b128 v[114:117], v242 offset:16384
	ds_read_b128 v[130:133], v242 offset:17408
	ds_read_b128 v[134:137], v242 offset:18432
	ds_read_b128 v[146:149], v242 offset:19456
	ds_read_b128 v[172:175], v242 offset:20480
	ds_read_b128 v[190:193], v242 offset:21504
	ds_read_b128 v[194:197], v242 offset:22528
	ds_read_b128 v[198:201], v242 offset:23552
	global_load_lds_dwordx4 v[248:249], off
	v_lshl_add_u64 v[236:237], s[52:53], 0, v[178:179]
	s_mov_b32 m0, s54
	s_nop 0
	global_load_lds_dwordx4 v[236:237], off
	s_barrier
	s_waitcnt lgkmcnt(0)
	s_waitcnt lgkmcnt(0)
	s_nop 0
	v_mfma_f32_16x16x32_bf16 v[94:97], v[42:45], v[114:117], v[94:97]
	v_mfma_f32_16x16x32_bf16 v[90:93], v[50:53], v[114:117], v[90:93]
	v_mfma_f32_16x16x32_bf16 v[78:81], v[42:45], v[134:137], v[78:81]
	v_mfma_f32_16x16x32_bf16 v[66:69], v[50:53], v[134:137], v[66:69]
	v_mfma_f32_16x16x32_bf16 v[30:33], v[42:45], v[172:175], v[30:33]
	v_mfma_f32_16x16x32_bf16 v[26:29], v[50:53], v[172:175], v[26:29]
	v_mfma_f32_16x16x32_bf16 v[14:17], v[42:45], v[194:197], v[14:17]
	v_mfma_f32_16x16x32_bf16 v[10:13], v[50:53], v[194:197], v[10:13]
	v_mfma_f32_16x16x32_bf16 v[94:97], v[46:49], v[130:133], v[94:97]
	v_mfma_f32_16x16x32_bf16 v[90:93], v[54:57], v[130:133], v[90:93]
	v_mfma_f32_16x16x32_bf16 v[78:81], v[46:49], v[146:149], v[78:81]
	v_mfma_f32_16x16x32_bf16 v[66:69], v[54:57], v[146:149], v[66:69]
	v_mfma_f32_16x16x32_bf16 v[30:33], v[46:49], v[190:193], v[30:33]
	v_mfma_f32_16x16x32_bf16 v[26:29], v[54:57], v[190:193], v[26:29]
	v_mfma_f32_16x16x32_bf16 v[14:17], v[46:49], v[198:201], v[14:17]
	v_mfma_f32_16x16x32_bf16 v[10:13], v[54:57], v[198:201], v[10:13]
	s_barrier
	s_add_u32 s58, s36, 0x40000
	s_addc_u32 s59, s37, 0
	s_add_i32 s56, s56, s26
	v_lshl_add_u64 v[42:43], s[58:59], 0, v[180:181]
	s_mov_b32 m0, s56
	s_nop 0
	global_load_lds_dwordx4 v[42:43], off
	v_lshl_add_u64 v[42:43], s[58:59], 0, v[176:177]
	s_add_i32 m0, s56, 0x2000
	s_nop 0
	global_load_lds_dwordx4 v[42:43], off
	s_cmp_lg_u32 s24, -2
	s_cbranch_scc1 .Lrx_s5_std
	s_cmp_lt_u32 s95, 2
	s_cbranch_scc1 .Lrx_s5_std
	s_waitcnt vmcnt(22)
	s_branch .Lrx_s5_done

; #define PG8_STAGE(bufoff, gbase, voff) do { _Pragma("unroll") for (int _i = 0; _i < 2; ++_i) \
;         __builtin_amdgcn_global_load_lds((const unsigned*)((const char*)(gbase) + (voff)[_i]), (LAS unsigned*)(lds + (bufoff) + ldsw + _i * 8192), 16, 0, 0); } while (0)
; #define PG8_LDA(dst, b, h) do { _Pragma("unroll") for (int m = 0; m < 4; ++m) _Pragma("unroll") for (int k = 0; k < 2; ++k) dst[m][k] = *(const LAS bf16x8*)(lds + PG8_SA(b, h) + aoff + m * 2048 + k * 1024); } while (0)
; #define PG8_LDB(dst, b, h) do { _Pragma("unroll") for (int n = 0; n < 2; ++n) _Pragma("unroll") for (int k = 0; k < 2; ++k) dst[n][k] = *(const LAS bf16x8*)(lds + PG8_SB(b, h) + boff + n * 2048 + k * 1024); } while (0)
; #define PG8_MMA(ai, bj, At, Bt) do { __builtin_amdgcn_s_setprio(1); _Pragma("unroll") for (int m = 0; m < 4; ++m) _Pragma("unroll") for (int n = 0; n < 2; ++n) _Pragma("unroll") for (int k = 0; k < 2; ++k) \
;         acc[ai][bj][m][n] = __builtin_amdgcn_mfma_f32_16x16x32_bf16(Bt[n][k], At[m][k], acc[ai][bj][m][n], 0, 0, 0); __builtin_amdgcn_s_setprio(0); } while (0)
; #define PG8_WAIT_V(n) asm volatile("s_waitcnt vmcnt(" #n ")" ::: "memory")
; #define PG8_WAIT_L(n) asm volatile("s_waitcnt lgkmcnt(" #n ")" ::: "memory")
; #define PG8_BAR __builtin_amdgcn_s_barrier()
; #define PG8_SCHED __builtin_amdgcn_sched_barrier(0)
; template <class Epi>
; __device__ __forceinline__ void gemm_phase(LAS unsigned char* lds, const Gemm g, const StaticOrder& S, const Epi& E) {
;     ...
;             PG8_WAIT_V(6); PG8_BAR; PG8_MMA(1, 1, At, B1); PG8_BAR;
;             PG8_LDB(B0, 1, 0); PG8_SCHED; PG8_LDA(At, 1, 0); PG8_STAGE(PG8_SA(0, 1), a2 + hstep, voffA);
;             PG8_WAIT_L(8); PG8_BAR; PG8_WAIT_L(0); PG8_MMA(0, 0, At, B0); PG8_BAR; PG8_SCHED;
;             PG8_LDB(B1, 1, 1); PG8_STAGE(PG8_SB(1, 0), b3, voffB);
;             PG8_BAR; PG8_WAIT_L(0); PG8_MMA(0, 1, At, B1); PG8_BAR;
;             PG8_LDA(At, 1, 1); PG8_STAGE(PG8_SA(1, 0), a3, voffA);
;             PG8_BAR; PG8_WAIT_L(0); PG8_MMA(1, 0, At, B0); PG8_BAR; PG8_SCHED;
.Lrx_s5_done:
	s_barrier
	v_mfma_f32_16x16x32_bf16 v[34:37], v[202:205], v[134:137], v[34:37]
	v_mfma_f32_16x16x32_bf16 v[38:41], v[210:213], v[134:137], v[38:41]
	v_mfma_f32_16x16x32_bf16 v[18:21], v[202:205], v[172:175], v[18:21]
	v_mfma_f32_16x16x32_bf16 v[22:25], v[210:213], v[172:175], v[22:25]
	v_mfma_f32_16x16x32_bf16 v[2:5], v[202:205], v[194:197], v[2:5]
	v_mfma_f32_16x16x32_bf16 v[6:9], v[210:213], v[194:197], v[6:9]
	v_mfma_f32_16x16x32_bf16 v[42:45], v[202:205], v[114:117], v[86:89]
	v_mfma_f32_16x16x32_bf16 v[46:49], v[210:213], v[114:117], v[82:85]
	v_mfma_f32_16x16x32_bf16 v[34:37], v[206:209], v[146:149], v[34:37]
	v_mfma_f32_16x16x32_bf16 v[38:41], v[214:217], v[146:149], v[38:41]
	v_mfma_f32_16x16x32_bf16 v[18:21], v[206:209], v[190:193], v[18:21]
	v_mfma_f32_16x16x32_bf16 v[22:25], v[214:217], v[190:193], v[22:25]
	v_mfma_f32_16x16x32_bf16 v[2:5], v[206:209], v[198:201], v[2:5]
	v_mfma_f32_16x16x32_bf16 v[6:9], v[214:217], v[198:201], v[6:9]
	v_mfma_f32_16x16x32_bf16 v[42:45], v[206:209], v[130:133], v[42:45]
	v_mfma_f32_16x16x32_bf16 v[46:49], v[214:217], v[130:133], v[46:49]
	s_add_i32 s56, 0, 0x18000
	v_add_u32_e32 v0, s56, v171
	s_barrier
	ds_read_b128 v[50:53], v0
	ds_read_b128 v[54:57], v0 offset:1024
	ds_read_b128 v[82:85], v0 offset:2048
	ds_read_b128 v[86:89], v0 offset:3072
	s_add_u32 s52, s52, 0x40000
	s_addc_u32 s53, s53, 0
	s_mov_b32 m0, s55
	v_lshl_add_u64 v[146:147], s[52:53], 0, v[182:183]
	ds_read_b128 v[114:117], v242 offset:32768
	ds_read_b128 v[130:133], v242 offset:33792
	ds_read_b128 v[134:137], v242 offset:34816
	ds_read_b128 v[172:175], v242 offset:35840
	ds_read_b128 v[190:193], v242 offset:36864
	ds_read_b128 v[194:197], v242 offset:37888
	ds_read_b128 v[198:201], v242 offset:38912
	ds_read_b128 v[202:205], v242 offset:39936
	global_load_lds_dwordx4 v[146:147], off
	v_lshl_add_u64 v[146:147], s[52:53], 0, v[178:179]
	s_mov_b32 m0, s70
	s_nop 0
	global_load_lds_dwordx4 v[146:147], off
	s_waitcnt lgkmcnt(8)
	s_barrier
	s_waitcnt lgkmcnt(0)
	s_waitcnt lgkmcnt(0)
	v_mfma_f32_16x16x32_bf16 v[146:149], v[50:53], v[114:117], v[158:161]
	v_mfma_f32_16x16x32_bf16 v[158:161], v[54:57], v[130:133], v[146:149]
	v_mfma_f32_16x16x32_bf16 v[146:149], v[82:85], v[114:117], v[154:157]
	v_mfma_f32_16x16x32_bf16 v[142:145], v[50:53], v[134:137], v[142:145]
	v_mfma_f32_16x16x32_bf16 v[138:141], v[82:85], v[134:137], v[138:141]
	v_mfma_f32_16x16x32_bf16 v[126:129], v[50:53], v[190:193], v[126:129]
	v_mfma_f32_16x16x32_bf16 v[122:125], v[82:85], v[190:193], v[122:125]
	v_mfma_f32_16x16x32_bf16 v[110:113], v[50:53], v[198:201], v[110:113]
	v_mfma_f32_16x16x32_bf16 v[106:109], v[82:85], v[198:201], v[106:109]
	v_mfma_f32_16x16x32_bf16 v[154:157], v[86:89], v[130:133], v[146:149]
	v_mfma_f32_16x16x32_bf16 v[142:145], v[54:57], v[172:175], v[142:145]
	v_mfma_f32_16x16x32_bf16 v[138:141], v[86:89], v[172:175], v[138:141]
	v_mfma_f32_16x16x32_bf16 v[126:129], v[54:57], v[194:197], v[126:129]
	v_mfma_f32_16x16x32_bf16 v[122:125], v[86:89], v[194:197], v[122:125]
	v_mfma_f32_16x16x32_bf16 v[110:113], v[54:57], v[202:205], v[110:113]
	v_mfma_f32_16x16x32_bf16 v[106:109], v[86:89], v[202:205], v[106:109]
	s_barrier
	s_add_i32 s52, 0, 0x1c000
	s_add_i32 s53, s56, s26
	v_add_u32_e32 v0, s52, v171
	v_lshl_add_u64 v[146:147], v[222:223], 0, s[28:29]
	s_mov_b32 m0, s53
	ds_read_b128 v[206:209], v0
	ds_read_b128 v[210:213], v0 offset:1024
	ds_read_b128 v[214:217], v0 offset:2048
	ds_read_b128 v[218:221], v0 offset:3072
	global_load_lds_dwordx4 v[146:147], off
	v_lshl_add_u64 v[146:147], v[246:247], 0, s[28:29]
	s_add_i32 m0, s53, 0x2000
	s_nop 0
	global_load_lds_dwordx4 v[146:147], off
	s_barrier
	s_waitcnt lgkmcnt(0)
	s_waitcnt lgkmcnt(0)
	v_mfma_f32_16x16x32_bf16 v[146:149], v[206:209], v[114:117], v[150:153]
	v_mfma_f32_16x16x32_bf16 v[58:61], v[214:217], v[114:117], v[58:61]
	v_mfma_f32_16x16x32_bf16 v[150:153], v[210:213], v[130:133], v[146:149]
	v_mfma_f32_16x16x32_bf16 v[146:149], v[218:221], v[130:133], v[58:61]
	v_mfma_f32_16x16x32_bf16 v[58:61], v[206:209], v[134:137], v[62:65]
	v_mfma_f32_16x16x32_bf16 v[130:133], v[210:213], v[172:175], v[58:61]
	v_mfma_f32_16x16x32_bf16 v[58:61], v[214:217], v[134:137], v[70:73]
	v_mfma_f32_16x16x32_bf16 v[134:137], v[218:221], v[172:175], v[58:61]
	v_mfma_f32_16x16x32_bf16 v[58:61], v[206:209], v[190:193], v[74:77]
	v_mfma_f32_16x16x32_bf16 v[114:117], v[210:213], v[194:197], v[58:61]
	v_mfma_f32_16x16x32_bf16 v[58:61], v[214:217], v[190:193], v[118:121]
	v_mfma_f32_16x16x32_bf16 v[118:121], v[218:221], v[194:197], v[58:61]
	v_mfma_f32_16x16x32_bf16 v[58:61], v[206:209], v[198:201], v[98:101]
	v_mfma_f32_16x16x32_bf16 v[98:101], v[210:213], v[202:205], v[58:61]
	v_mfma_f32_16x16x32_bf16 v[58:61], v[214:217], v[198:201], v[102:105]
	v_mfma_f32_16x16x32_bf16 v[102:105], v[218:221], v[202:205], v[58:61]
	s_mov_b32 m0, s93
	v_lshl_add_u64 v[202:203], v[248:249], 0, s[28:29]
	s_waitcnt vmcnt(10)
	s_barrier
	s_nop 2
	ds_read_b128 v[58:61], v242 offset:49152
	ds_read_b128 v[62:65], v242 offset:50176
	ds_read_b128 v[70:73], v242 offset:51200
	ds_read_b128 v[74:77], v242 offset:52224
	ds_read_b128 v[172:175], v242 offset:53248
	ds_read_b128 v[190:193], v242 offset:54272
	ds_read_b128 v[194:197], v242 offset:55296
	ds_read_b128 v[198:201], v242 offset:56320
	global_load_lds_dwordx4 v[202:203], off
	v_lshl_add_u64 v[202:203], v[236:237], 0, s[28:29]
	s_mov_b32 m0, s94
	s_nop 0
	global_load_lds_dwordx4 v[202:203], off
	s_barrier
; #define PG8_WAIT_V(n) asm volatile("s_waitcnt vmcnt(" #n ")" ::: "memory")
; template <class Epi>
; __device__ __forceinline__ void gemm_phase(LAS unsigned char* lds, const Gemm g, const StaticOrder& S, const Epi& E) {
;     ...
;             PG8_BAR; PG8_WAIT_L(0); PG8_MMA(1, 0, At, B0); PG8_BAR; PG8_SCHED;
;             PG8_STAGE(PG8_SB(1, 1), b3 + hstep, voffB);
;             PG8_WAIT_V(6); PG8_BAR; PG8_MMA(1, 1, At, B1); PG8_BAR;
;     __device__ __forceinline__ void operator()(const f32x4 (&acc)[2][2][4][2], const Unit& u, int wr, int wc, int fr, int fq) const {
;         const int row0 = u.pm * BM + wr * 64 + fr, f0 = u.pn * HALF + wc * 32 + 8 * fq;
;         float w0[8], w1[8], w2[8], bb[8];
;         *(f32x4*)w0 = *(const f32x4*)(cw + f0); *(f32x4*)(w0 + 4) = *(const f32x4*)(cw + f0 + 4);
;         *(f32x4*)w1 = *(const f32x4*)(cw + DFF + f0); *(f32x4*)(w1 + 4) = *(const f32x4*)(cw + DFF + f0 + 4);
;         *(f32x4*)w2 = *(const f32x4*)(cw + 2 * DFF + f0); *(f32x4*)(w2 + 4) = *(const f32x4*)(cw + 2 * DFF + f0 + 4);
;         *(f32x4*)bb = *(const f32x4*)(cb + f0); *(f32x4*)(bb + 4) = *(const f32x4*)(cb + f0 + 4);
;         u64 rv[2][4];
; #pragma unroll
;         for (int ai = 0; ai < 2; ++ai)
; #pragma unroll
;             for (int m = 0; m < 4; ++m) rv[ai][m] = rss[row0 + ai * HALF + m * 16];
; #pragma unroll
;         for (int ai = 0; ai < 2; ++ai) {
;             float gp[8];
; #pragma unroll
;             for (int e = 0; e < 8; ++e) gp[e] = 0.f;
; #pragma unroll
;             for (int m = 0; m < 4; ++m) {
;                 const int row = row0 + ai * HALF + m * 16;
;                 const float rs = rstd_fix(rv[ai][m]);
;                 float g[8], up[8], o[8];
;                 { const f32x4 g0 = acc[ai][0][m][0] * rs, g1 = acc[ai][0][m][1] * rs, u0 = acc[ai][1][m][0] * rs, u1 = acc[ai][1][m][1] * rs;
; #pragma unroll
;                   for (int i = 0; i < 4; ++i) { g[i] = g0[i]; g[4 + i] = g1[i]; up[i] = u0[i]; up[4 + i] = u1[i]; } }
; #pragma unroll
;                 for (int e2 = 0; e2 < 4; ++e2) {
;                     const int e = 2 * e2;
;                     const f32x2 gv = {g[e], g[e + 1]};
;                     const f32x2 g1v = {dpp_shr<1>(dpp_ror<1>(gp[e]), g[e]), dpp_shr<1>(dpp_ror<1>(gp[e + 1]), g[e + 1])};
;                     const f32x2 g2v = {dpp_shr<2>(dpp_ror<2>(gp[e]), g[e]), dpp_shr<2>(dpp_ror<2>(gp[e + 1]), g[e + 1])};
	s_waitcnt lgkmcnt(0)
	s_waitcnt lgkmcnt(0)
	s_nop 0
	v_mfma_f32_16x16x32_bf16 v[94:97], v[50:53], v[58:61], v[94:97]
	v_mfma_f32_16x16x32_bf16 v[90:93], v[82:85], v[58:61], v[90:93]
	v_mfma_f32_16x16x32_bf16 v[78:81], v[50:53], v[70:73], v[78:81]
	v_mfma_f32_16x16x32_bf16 v[66:69], v[82:85], v[70:73], v[66:69]
	v_mfma_f32_16x16x32_bf16 v[30:33], v[50:53], v[172:175], v[30:33]
	v_mfma_f32_16x16x32_bf16 v[26:29], v[82:85], v[172:175], v[26:29]
	v_mfma_f32_16x16x32_bf16 v[14:17], v[50:53], v[194:197], v[14:17]
	v_mfma_f32_16x16x32_bf16 v[10:13], v[82:85], v[194:197], v[10:13]
	v_mfma_f32_16x16x32_bf16 v[94:97], v[54:57], v[62:65], v[94:97]
	v_mfma_f32_16x16x32_bf16 v[90:93], v[86:89], v[62:65], v[90:93]
	v_mfma_f32_16x16x32_bf16 v[78:81], v[54:57], v[74:77], v[78:81]
	v_mfma_f32_16x16x32_bf16 v[66:69], v[86:89], v[74:77], v[66:69]
	v_mfma_f32_16x16x32_bf16 v[30:33], v[54:57], v[190:193], v[30:33]
	v_mfma_f32_16x16x32_bf16 v[26:29], v[86:89], v[190:193], v[26:29]
	v_mfma_f32_16x16x32_bf16 v[14:17], v[54:57], v[198:201], v[14:17]
	v_mfma_f32_16x16x32_bf16 v[10:13], v[86:89], v[198:201], v[10:13]
	s_barrier
	s_add_u32 s36, s36, 0x40080
	s_addc_u32 s37, s37, 0
	s_add_i32 s52, s52, s26
	v_lshl_add_u64 v[50:51], s[36:37], 0, v[180:181]
	s_mov_b32 m0, s52
	s_nop 0
	global_load_lds_dwordx4 v[50:51], off
	v_lshl_add_u64 v[50:51], s[36:37], 0, v[176:177]
	s_add_i32 m0, s52, 0x2000
	s_nop 0
	global_load_lds_dwordx4 v[50:51], off
	s_waitcnt vmcnt(6)
	s_barrier
	v_mfma_f32_16x16x32_bf16 v[42:45], v[206:209], v[58:61], v[42:45]
	v_mfma_f32_16x16x32_bf16 v[86:89], v[210:213], v[62:65], v[42:45]
	v_mfma_f32_16x16x32_bf16 v[42:45], v[214:217], v[58:61], v[46:49]
	v_mfma_f32_16x16x32_bf16 v[34:37], v[206:209], v[70:73], v[34:37]
	v_mfma_f32_16x16x32_bf16 v[38:41], v[214:217], v[70:73], v[38:41]
	v_mfma_f32_16x16x32_bf16 v[18:21], v[206:209], v[172:175], v[18:21]
	v_mfma_f32_16x16x32_bf16 v[22:25], v[214:217], v[172:175], v[22:25]
	v_mfma_f32_16x16x32_bf16 v[2:5], v[206:209], v[194:197], v[2:5]
	v_mfma_f32_16x16x32_bf16 v[6:9], v[214:217], v[194:197], v[6:9]
	v_mfma_f32_16x16x32_bf16 v[82:85], v[218:221], v[62:65], v[42:45]
	v_mfma_f32_16x16x32_bf16 v[34:37], v[210:213], v[74:77], v[34:37]
	v_mfma_f32_16x16x32_bf16 v[38:41], v[218:221], v[74:77], v[38:41]
	v_mfma_f32_16x16x32_bf16 v[18:21], v[210:213], v[190:193], v[18:21]
	v_mfma_f32_16x16x32_bf16 v[22:25], v[218:221], v[190:193], v[22:25]
	v_mfma_f32_16x16x32_bf16 v[2:5], v[210:213], v[198:201], v[2:5]
	v_mfma_f32_16x16x32_bf16 v[6:9], v[218:221], v[198:201], v[6:9]
	s_add_i32 s24, s24, 2
	s_add_u32 s0, s0, 0x100
	s_addc_u32 s1, s1, 0
	s_add_u32 vcc_lo, vcc_lo, 0x100
	s_addc_u32 vcc_hi, vcc_hi, 0
	s_cmp_gt_u32 s24, 13
	s_barrier
	s_cbranch_scc0 .LBB0_211
	s_setprio 0
	s_lshl_b32 s2, s2, 8
	s_add_i32 s2, s2, s71
	v_lshl_or_b32 v190, s3, 7, v241
	v_or_b32_e32 v196, s2, v168
	v_ashrrev_i32_e32 v191, 31, v190
	v_ashrrev_i32_e32 v197, 31, v196
	s_and_b32 s24, s95, 1
	s_lshl_b32 s24, s24, 12
	s_add_i32 s24, s24, 0x20400
	v_lshl_add_u32 v173, v241, 2, s24
	v_add_lshl_u32 v172, s71, v168, 3
	v_add_u32_e32 v172, s24, v172
	ds_read_b128 v[42:45], v173
	ds_read_b128 v[58:61], v173 offset:16
	ds_read_b128 v[46:49], v173 offset:512
	ds_read_b128 v[62:65], v173 offset:528
	ds_read_b128 v[50:53], v173 offset:1024
	ds_read_b128 v[70:73], v173 offset:1040
	ds_read_b128 v[54:57], v173 offset:1536
	ds_read_b128 v[74:77], v173 offset:1552
	ds_read_b64 v[174:175], v172 offset:2048
	ds_read_b64 v[206:207], v172 offset:2176
	ds_read_b64 v[204:205], v172 offset:2304
	ds_read_b64 v[202:203], v172 offset:2432
	ds_read_b64 v[200:201], v172 offset:3072
	ds_read_b64 v[198:199], v172 offset:3200
	ds_read_b64 v[194:195], v172 offset:3328
	ds_read_b64 v[192:193], v172 offset:3456
	v_mov_b32_e32 v217, v1
	v_mov_b32_e32 v219, v1
	s_waitcnt lgkmcnt(0)
	v_ffbh_u32_e32 v0, v175
	v_min_u32_e32 v0, 32, v0
	v_lshlrev_b64 v[172:173], v0, v[174:175]
	v_min_u32_e32 v172, 1, v172
	v_or_b32_e32 v172, v173, v172
	v_cvt_f32_u32_e32 v172, v172
	v_sub_u32_e32 v0, 32, v0
	v_mov_b32_dpp v217, v217 row_ror:1 row_mask:0xf bank_mask:0xf
	v_mov_b32_dpp v219, v219 row_ror:2 row_mask:0xf bank_mask:0xf
	v_ldexp_f32 v0, v172, v0
	v_fmamk_f32 v0, v0, 0x30800000, v162
	v_cmp_gt_f32_e32 vcc, s79, v0
	v_mul_f32_e32 v172, 0x4b800000, v0
	v_mov_b32_e32 v212, v217
	v_cndmask_b32_e32 v0, v0, v172, vcc
	v_rsq_f32_e32 v0, v0
	v_mov_b32_e32 v213, v217
	v_mov_b32_e32 v214, v219
	v_mov_b32_e32 v215, v219
	v_mul_f32_e32 v172, 0x45800000, v0
	v_cndmask_b32_e32 v0, v0, v172, vcc
	v_pk_mul_f32 v[158:159], v[158:159], v[0:1] op_sel_hi:[1,0]
	v_pk_mul_f32 v[154:155], v[154:155], v[0:1] op_sel_hi:[1,0]
	v_pk_mul_f32 v[208:209], v[150:151], v[0:1] op_sel_hi:[1,0]
	v_pk_mul_f32 v[210:211], v[146:147], v[0:1] op_sel_hi:[1,0]
	v_pk_mul_f32 v[150:151], v[160:161], v[0:1] op_sel_hi:[1,0]
	v_pk_mul_f32 v[146:147], v[156:157], v[0:1] op_sel_hi:[1,0]
	v_mov_b32_e32 v156, v217
	v_mov_b32_e32 v157, v217
	v_mov_b32_e32 v160, v219
	v_mov_b32_e32 v161, v219
	v_mov_b32_e32 v220, v217
	v_mov_b32_e32 v221, v217
	v_mov_b32_e32 v222, v219
	v_mov_b32_e32 v223, v219
	v_mov_b32_e32 v216, v217
	v_mov_b32_e32 v218, v219
	v_pk_mul_f32 v[152:153], v[152:153], v[0:1] op_sel_hi:[1,0]
	v_pk_mul_f32 v[148:149], v[148:149], v[0:1] op_sel_hi:[1,0]
	v_mov_b32_dpp v156, v158 row_shr:1 row_mask:0xf bank_mask:0xf
	v_mov_b32_dpp v157, v159 row_shr:1 row_mask:0xf bank_mask:0xf
	v_mov_b32_dpp v160, v158 row_shr:2 row_mask:0xf bank_mask:0xf
	v_mov_b32_dpp v161, v159 row_shr:2 row_mask:0xf bank_mask:0xf
	v_mov_b32_dpp v212, v150 row_shr:1 row_mask:0xf bank_mask:0xf
	v_mov_b32_dpp v213, v151 row_shr:1 row_mask:0xf bank_mask:0xf
	v_mov_b32_dpp v214, v150 row_shr:2 row_mask:0xf bank_mask:0xf
	v_mov_b32_dpp v215, v151 row_shr:2 row_mask:0xf bank_mask:0xf
	v_mov_b32_dpp v220, v154 row_shr:1 row_mask:0xf bank_mask:0xf
	v_mov_b32_dpp v221, v155 row_shr:1 row_mask:0xf bank_mask:0xf
	v_mov_b32_dpp v222, v154 row_shr:2 row_mask:0xf bank_mask:0xf
	v_mov_b32_dpp v223, v155 row_shr:2 row_mask:0xf bank_mask:0xf
	v_mov_b32_dpp v216, v146 row_shr:1 row_mask:0xf bank_mask:0xf
	v_mov_b32_dpp v217, v147 row_shr:1 row_mask:0xf bank_mask:0xf
	v_mov_b32_dpp v218, v146 row_shr:2 row_mask:0xf bank_mask:0xf
	v_mov_b32_dpp v219, v147 row_shr:2 row_mask:0xf bank_mask:0xf
	s_and_saveexec_b64 s[0:1], s[40:41]
	s_xor_b64 s[0:1], exec, s[0:1]
	s_cbranch_execz .LBB0_214
; __device__ __forceinline__ u32x4 pack8(const float* f) { u32x4 w; w.x = pk2(f[0], f[1]); w.y = pk2(f[2], f[3]); w.z = pk2(f[4], f[5]); w.w = pk2(f[6], f[7]); return w; }
; template <int N> __device__ __forceinline__ float dpp_shr(float old, float src) { return __int_as_float(__builtin_amdgcn_update_dpp(__float_as_int(old), __float_as_int(src), 0x110 + N, 0xf, 0xf, false)); }
; template <int N> __device__ __forceinline__ float dpp_ror(float src) { return __int_as_float(__builtin_amdgcn_update_dpp(0, __float_as_int(src), 0x120 + N, 0xf, 0xf, false)); }
;     __device__ __forceinline__ void operator()(const f32x4 (&acc)[2][2][4][2], const Unit& u, int wr, int wc, int fr, int fq) const {
;     ...
;                 for (int e2 = 0; e2 < 4; ++e2) {
;                     const int e = 2 * e2;
;                     const f32x2 gv = {g[e], g[e + 1]};
;                     const f32x2 g1v = {dpp_shr<1>(dpp_ror<1>(gp[e]), g[e]), dpp_shr<1>(dpp_ror<1>(gp[e + 1]), g[e + 1])};
;                     const f32x2 g2v = {dpp_shr<2>(dpp_ror<2>(gp[e]), g[e]), dpp_shr<2>(dpp_ror<2>(gp[e + 1]), g[e + 1])};
;                     const f32x2 w0v = {w0[e], w0[e + 1]}, w1v = {w1[e], w1[e + 1]}, w2v = {w2[e], w2[e + 1]}, bbv = {bb[e], bb[e + 1]}, upv = {up[e], up[e + 1]};
;                     const f32x2 y = __builtin_elementwise_fma(w0v, g2v, __builtin_elementwise_fma(w1v, g1v, __builtin_elementwise_fma(w2v, gv, bbv)));
;                     const f32x2 z = y * __builtin_elementwise_fma(y * y, (f32x2){0.1029432397f, 0.1029432397f}, (f32x2){2.302208198f, 2.302208198f});
;                     f32x2 d; d.x = __builtin_amdgcn_exp2f(z.x); d.y = __builtin_amdgcn_exp2f(z.y);
;                     d = d + 1.0f;
;                     f32x2 r; r.x = __builtin_amdgcn_rcpf(d.x); r.y = __builtin_amdgcn_rcpf(d.y);
;                     const f32x2 ov = __builtin_elementwise_fma(-y, r, y) * upv;
;                     o[e] = ov.x; o[e + 1] = ov.y;
;                 }
;                 if (m == 0 && fr < 2) {
;                     const size_t so = ((size_t)(row >> 6) * 2 + fr) * DFF + f0;
;                     *(u32x4*)(gs01 + so) = pack8(g); *(u32x4*)(us01 + so) = pack8(up);
;                 } else *(u32x4*)(act + (size_t)row * DFF + f0) = pack8(o);
	v_pk_fma_f32 v[172:173], v[72:73], v[146:147], v[76:77]
	s_mov_b32 s24, 0x40135761
	v_pk_fma_f32 v[172:173], v[64:65], v[216:217], v[172:173]
	v_mov_b64_e32 v[216:217], s[24:25]
	v_pk_fma_f32 v[172:173], v[60:61], v[218:219], v[172:173]
	s_mov_b32 s24, 0x3dd2d3e8
	v_pk_mul_f32 v[174:175], v[172:173], v[172:173]
	v_readlane_b32 s36, v252, 57
	v_pk_fma_f32 v[174:175], v[174:175], s[24:25], v[216:217] op_sel_hi:[1,0,0]
	v_readlane_b32 s37, v252, 58
	v_pk_mul_f32 v[174:175], v[172:173], v[174:175]
	s_movk_i32 s3, 0x1600
	v_exp_f32_e32 v174, v174
	v_exp_f32_e32 v175, v175
	s_nop 0
	v_pk_add_f32 v[174:175], v[174:175], 1.0 op_sel_hi:[1,0]
	s_nop 0
	v_rcp_f32_e32 v174, v174
	v_rcp_f32_e32 v175, v175
	s_nop 0
	v_pk_fma_f32 v[172:173], v[172:173], v[174:175], v[172:173] neg_lo:[1,0,0] neg_hi:[1,0,0]
	s_nop 0
	v_pk_mul_f32 v[148:149], v[148:149], v[172:173]
	v_pk_fma_f32 v[172:173], v[70:71], v[154:155], v[74:75]
	s_nop 0
	v_pk_fma_f32 v[172:173], v[62:63], v[220:221], v[172:173]
	s_nop 0
	v_pk_fma_f32 v[172:173], v[58:59], v[222:223], v[172:173]
	s_nop 0
	v_pk_mul_f32 v[174:175], v[172:173], v[172:173]
	s_nop 0
	v_pk_fma_f32 v[174:175], v[174:175], s[24:25], v[216:217] op_sel_hi:[1,0,0]
	s_nop 0
	v_pk_mul_f32 v[174:175], v[172:173], v[174:175]
	s_nop 0
	v_exp_f32_e32 v174, v174
	v_exp_f32_e32 v175, v175
	s_nop 0
	v_pk_add_f32 v[174:175], v[174:175], 1.0 op_sel_hi:[1,0]
	s_nop 0
	v_rcp_f32_e32 v174, v174
	v_rcp_f32_e32 v175, v175
	s_nop 0
	v_pk_fma_f32 v[172:173], v[172:173], v[174:175], v[172:173] neg_lo:[1,0,0] neg_hi:[1,0,0]
	s_nop 0
	v_pk_mul_f32 v[174:175], v[210:211], v[172:173]
	v_pk_fma_f32 v[172:173], v[52:53], v[150:151], v[56:57]
	s_nop 0
	v_pk_fma_f32 v[172:173], v[48:49], v[212:213], v[172:173]
	s_nop 0
	v_pk_fma_f32 v[172:173], v[44:45], v[214:215], v[172:173]
	s_nop 0
	v_pk_mul_f32 v[210:211], v[172:173], v[172:173]
	s_nop 0
	v_pk_fma_f32 v[210:211], v[210:211], s[24:25], v[216:217] op_sel_hi:[1,0,0]
	s_nop 0
	v_pk_mul_f32 v[210:211], v[172:173], v[210:211]
	s_nop 0
	v_exp_f32_e32 v210, v210
	v_exp_f32_e32 v211, v211
	s_nop 0
	v_pk_add_f32 v[210:211], v[210:211], 1.0 op_sel_hi:[1,0]
	s_nop 0
	v_rcp_f32_e32 v210, v210
	v_rcp_f32_e32 v211, v211
	s_nop 0
	v_pk_fma_f32 v[172:173], v[172:173], v[210:211], v[172:173] neg_lo:[1,0,0] neg_hi:[1,0,0]
	s_nop 0
	v_pk_mul_f32 v[152:153], v[152:153], v[172:173]
	v_pk_fma_f32 v[172:173], v[50:51], v[158:159], v[54:55]
	s_nop 0
	v_pk_fma_f32 v[156:157], v[46:47], v[156:157], v[172:173]
	s_nop 0
	v_pk_fma_f32 v[156:157], v[42:43], v[160:161], v[156:157]
	s_nop 0
	v_pk_mul_f32 v[160:161], v[156:157], v[156:157]
	s_nop 0
	v_pk_fma_f32 v[160:161], v[160:161], s[24:25], v[216:217] op_sel_hi:[1,0,0]
	s_nop 0
	v_pk_mul_f32 v[160:161], v[156:157], v[160:161]
	s_nop 0
	v_exp_f32_e32 v160, v160
	v_exp_f32_e32 v161, v161
	s_nop 0
	v_pk_add_f32 v[160:161], v[160:161], 1.0 op_sel_hi:[1,0]
	s_nop 0
	v_rcp_f32_e32 v160, v160
	v_rcp_f32_e32 v161, v161
	s_nop 0
	v_pk_fma_f32 v[156:157], v[156:157], v[160:161], v[156:157] neg_lo:[1,0,0] neg_hi:[1,0,0]
	s_nop 0
	v_pk_mul_f32 v[156:157], v[208:209], v[156:157]
	s_nop 0
	v_cvt_pk_bf16_f32 v172, v156, v157
	v_cvt_pk_bf16_f32 v173, v152, v153
	v_cvt_pk_bf16_f32 v174, v174, v175
	v_cvt_pk_bf16_f32 v175, v148, v149
	v_mov_b64_e32 v[148:149], s[36:37]
	v_mad_i64_i32 v[148:149], s[36:37], v196, s3, v[148:149]
	v_lshl_add_u64 v[148:149], v[190:191], 1, v[148:149]
	global_store_dwordx4 v[148:149], v[172:175], off nt

; #define PG8_STAGE(bufoff, gbase, voff) do { _Pragma("unroll") for (int _i = 0; _i < 2; ++_i) \
;         __builtin_amdgcn_global_load_lds((const unsigned*)((const char*)(gbase) + (voff)[_i]), (LAS unsigned*)(lds + (bufoff) + ldsw + _i * 8192), 16, 0, 0); } while (0)
; #define PG8_LDA(dst, b, h) do { _Pragma("unroll") for (int m = 0; m < 4; ++m) _Pragma("unroll") for (int k = 0; k < 2; ++k) dst[m][k] = *(const LAS bf16x8*)(lds + PG8_SA(b, h) + aoff + m * 2048 + k * 1024); } while (0)
; #define PG8_LDB(dst, b, h) do { _Pragma("unroll") for (int n = 0; n < 2; ++n) _Pragma("unroll") for (int k = 0; k < 2; ++k) dst[n][k] = *(const LAS bf16x8*)(lds + PG8_SB(b, h) + boff + n * 2048 + k * 1024); } while (0)
; #define PG8_MMA(ai, bj, At, Bt) do { __builtin_amdgcn_s_setprio(1); _Pragma("unroll") for (int m = 0; m < 4; ++m) _Pragma("unroll") for (int n = 0; n < 2; ++n) _Pragma("unroll") for (int k = 0; k < 2; ++k) \
;         acc[ai][bj][m][n] = __builtin_amdgcn_mfma_f32_16x16x32_bf16(Bt[n][k], At[m][k], acc[ai][bj][m][n], 0, 0, 0); __builtin_amdgcn_s_setprio(0); } while (0)
; #define PG8_WAIT_V(n) asm volatile("s_waitcnt vmcnt(" #n ")" ::: "memory")
; #define PG8_WAIT_L(n) asm volatile("s_waitcnt lgkmcnt(" #n ")" ::: "memory")
; #define PG8_BAR __builtin_amdgcn_s_barrier()
; #define PG8_SCHED __builtin_amdgcn_sched_barrier(0)
; template <class Epi>
; __device__ __forceinline__ void gemm_phase(LAS unsigned char* lds, const Gemm g, const StaticOrder& S, const Epi& E) {
;     ...
;             PG8_LDB(B0, 0, 0); PG8_SCHED; PG8_LDA(At, 0, 0); PG8_STAGE(PG8_SA(1, 1), a1 + hstep, voffA);
;             PG8_WAIT_L(8); PG8_BAR; PG8_WAIT_L(0); PG8_MMA(0, 0, At, B0); PG8_BAR; PG8_SCHED;
;             PG8_LDB(B1, 0, 1); PG8_STAGE(PG8_SB(0, 0), b2, voffB);
;             PG8_BAR; PG8_WAIT_L(0); PG8_MMA(0, 1, At, B1); PG8_BAR;
;             PG8_LDA(At, 0, 1); PG8_STAGE(PG8_SA(0, 0), a2, voffA);
;             PG8_BAR; PG8_WAIT_L(0); PG8_MMA(1, 0, At, B0); PG8_BAR; PG8_SCHED;
;             PG8_STAGE(PG8_SB(0, 1), b2 + hstep, voffB);
;             PG8_WAIT_V(6); PG8_BAR; PG8_MMA(1, 1, At, B1); PG8_BAR;
;             PG8_LDB(B0, 1, 0); PG8_SCHED; PG8_LDA(At, 1, 0); PG8_STAGE(PG8_SA(0, 1), a2 + hstep, voffA);
;             PG8_WAIT_L(8); PG8_BAR; PG8_WAIT_L(0); PG8_MMA(0, 0, At, B0); PG8_BAR; PG8_SCHED;
.Lprio_258:
.LBB0_258:
	s_add_u32 s46, s48, s50
	s_addc_u32 s47, s49, s51
	s_add_u32 s46, s46, 0x100
	s_addc_u32 s47, s47, 0
	s_add_u32 s52, s68, s50
	s_addc_u32 s53, s69, s51
	s_add_i32 s71, 0, 0x10000
	v_add_u32_e32 v140, s71, v143
	ds_read_b128 v[148:151], v140
	ds_read_b128 v[152:155], v140 offset:1024
	ds_read_b128 v[156:159], v140 offset:2048
	ds_read_b128 v[172:175], v140 offset:3072
	s_cmpk_eq_i32 s50, 0xb00
	s_cselect_b32 s47, s37, s47
	s_cselect_b32 s46, s36, s46
	s_cselect_b32 s53, s45, s53
	s_cselect_b32 s52, s44, s52
	v_lshl_add_u64 v[140:141], v[136:137], 0, s[50:51]
	s_add_i32 m0, s55, 0xc000
	ds_read_b128 v[178:181], v147
	ds_read_b128 v[182:185], v147 offset:1024
	ds_read_b128 v[186:189], v147 offset:2048
	ds_read_b128 v[190:193], v147 offset:3072
	ds_read_b128 v[194:197], v147 offset:4096
	ds_read_b128 v[198:201], v147 offset:5120
	ds_read_b128 v[202:205], v147 offset:6144
	ds_read_b128 v[206:209], v147 offset:7168
	global_load_lds_dwordx4 v[140:141], off
	v_lshl_add_u64 v[140:141], v[138:139], 0, s[50:51]
	s_add_i32 m0, s55, 0xe000
	s_nop 0
	global_load_lds_dwordx4 v[140:141], off
	s_waitcnt lgkmcnt(8)
	s_barrier
	s_waitcnt lgkmcnt(0)
	s_waitcnt lgkmcnt(0)
	s_nop 0
	v_mfma_f32_16x16x32_bf16 v[126:129], v[148:151], v[178:181], v[126:129]
	v_mfma_f32_16x16x32_bf16 v[122:125], v[156:159], v[178:181], v[122:125]
	v_mfma_f32_16x16x32_bf16 v[110:113], v[148:151], v[186:189], v[110:113]
	v_mfma_f32_16x16x32_bf16 v[106:109], v[156:159], v[186:189], v[106:109]
	v_mfma_f32_16x16x32_bf16 v[94:97], v[148:151], v[194:197], v[94:97]
	v_mfma_f32_16x16x32_bf16 v[90:93], v[156:159], v[194:197], v[90:93]
	v_mfma_f32_16x16x32_bf16 v[78:81], v[148:151], v[202:205], v[78:81]
	v_mfma_f32_16x16x32_bf16 v[74:77], v[156:159], v[202:205], v[74:77]
	v_mfma_f32_16x16x32_bf16 v[126:129], v[152:155], v[182:185], v[126:129]
	v_mfma_f32_16x16x32_bf16 v[122:125], v[172:175], v[182:185], v[122:125]
	v_mfma_f32_16x16x32_bf16 v[110:113], v[152:155], v[190:193], v[110:113]
	v_mfma_f32_16x16x32_bf16 v[106:109], v[172:175], v[190:193], v[106:109]
	v_mfma_f32_16x16x32_bf16 v[94:97], v[152:155], v[198:201], v[94:97]
	v_mfma_f32_16x16x32_bf16 v[90:93], v[172:175], v[198:201], v[90:93]
	v_mfma_f32_16x16x32_bf16 v[78:81], v[152:155], v[206:209], v[78:81]
	v_mfma_f32_16x16x32_bf16 v[74:77], v[172:175], v[206:209], v[74:77]
	s_barrier
	s_add_i32 s93, 0, 0x14000
	v_add_u32_e32 v140, s93, v143
	s_add_i32 s71, s71, s54
	ds_read_b128 v[210:213], v140
	ds_read_b128 v[214:217], v140 offset:1024
	ds_read_b128 v[218:221], v140 offset:2048
	ds_read_b128 v[246:249], v140 offset:3072
	v_lshl_add_u64 v[140:141], s[52:53], 0, v[0:1]
	s_mov_b32 m0, s71
	v_lshl_add_u64 v[160:161], s[52:53], 0, v[130:131]
	global_load_lds_dwordx4 v[140:141], off
	s_add_i32 m0, s71, 0x2000
	s_nop 0
	global_load_lds_dwordx4 v[160:161], off
	s_barrier
	s_waitcnt lgkmcnt(0)
	s_waitcnt lgkmcnt(0)
	v_mfma_f32_16x16x32_bf16 v[118:121], v[210:213], v[178:181], v[118:121]
	v_mfma_f32_16x16x32_bf16 v[114:117], v[218:221], v[178:181], v[114:117]
	v_mfma_f32_16x16x32_bf16 v[102:105], v[210:213], v[186:189], v[102:105]
	v_mfma_f32_16x16x32_bf16 v[98:101], v[218:221], v[186:189], v[98:101]
	v_mfma_f32_16x16x32_bf16 v[86:89], v[210:213], v[194:197], v[86:89]
	v_mfma_f32_16x16x32_bf16 v[82:85], v[218:221], v[194:197], v[82:85]
	v_mfma_f32_16x16x32_bf16 v[70:73], v[210:213], v[202:205], v[70:73]
	v_mfma_f32_16x16x32_bf16 v[66:69], v[218:221], v[202:205], v[66:69]
	v_mfma_f32_16x16x32_bf16 v[118:121], v[214:217], v[182:185], v[118:121]
	v_mfma_f32_16x16x32_bf16 v[114:117], v[246:249], v[182:185], v[114:117]
	v_mfma_f32_16x16x32_bf16 v[102:105], v[214:217], v[190:193], v[102:105]
	v_mfma_f32_16x16x32_bf16 v[98:101], v[246:249], v[190:193], v[98:101]
	v_mfma_f32_16x16x32_bf16 v[86:89], v[214:217], v[198:201], v[86:89]
	v_mfma_f32_16x16x32_bf16 v[82:85], v[246:249], v[198:201], v[82:85]
	v_mfma_f32_16x16x32_bf16 v[70:73], v[214:217], v[206:209], v[70:73]
	v_mfma_f32_16x16x32_bf16 v[66:69], v[246:249], v[206:209], v[66:69]
	s_mov_b32 m0, s55
	v_lshl_add_u64 v[222:223], s[46:47], 0, v[0:1]
	s_barrier
	ds_read_b128 v[178:181], v147 offset:16384
	ds_read_b128 v[182:185], v147 offset:17408
	ds_read_b128 v[186:189], v147 offset:18432
	ds_read_b128 v[190:193], v147 offset:19456
	ds_read_b128 v[194:197], v147 offset:20480
	ds_read_b128 v[198:201], v147 offset:21504
	ds_read_b128 v[202:205], v147 offset:22528
	ds_read_b128 v[206:209], v147 offset:23552
	global_load_lds_dwordx4 v[222:223], off
	v_lshl_add_u64 v[242:243], s[46:47], 0, v[130:131]
	s_mov_b32 m0, s58
	s_nop 0
	global_load_lds_dwordx4 v[242:243], off
	s_barrier
	s_waitcnt lgkmcnt(0)
	s_waitcnt lgkmcnt(0)
	s_nop 0
	v_mfma_f32_16x16x32_bf16 v[62:65], v[148:151], v[178:181], v[62:65]
	v_mfma_f32_16x16x32_bf16 v[58:61], v[156:159], v[178:181], v[58:61]
	v_mfma_f32_16x16x32_bf16 v[46:49], v[148:151], v[186:189], v[46:49]
	v_mfma_f32_16x16x32_bf16 v[42:45], v[156:159], v[186:189], v[42:45]
	v_mfma_f32_16x16x32_bf16 v[30:33], v[148:151], v[194:197], v[30:33]
	v_mfma_f32_16x16x32_bf16 v[26:29], v[156:159], v[194:197], v[26:29]
	v_mfma_f32_16x16x32_bf16 v[14:17], v[148:151], v[202:205], v[14:17]
	v_mfma_f32_16x16x32_bf16 v[10:13], v[156:159], v[202:205], v[10:13]
	v_mfma_f32_16x16x32_bf16 v[62:65], v[152:155], v[182:185], v[62:65]
	v_mfma_f32_16x16x32_bf16 v[58:61], v[172:175], v[182:185], v[58:61]
	v_mfma_f32_16x16x32_bf16 v[46:49], v[152:155], v[190:193], v[46:49]
	v_mfma_f32_16x16x32_bf16 v[42:45], v[172:175], v[190:193], v[42:45]
	v_mfma_f32_16x16x32_bf16 v[30:33], v[152:155], v[198:201], v[30:33]
	v_mfma_f32_16x16x32_bf16 v[26:29], v[172:175], v[198:201], v[26:29]
	v_mfma_f32_16x16x32_bf16 v[14:17], v[152:155], v[206:209], v[14:17]
	v_mfma_f32_16x16x32_bf16 v[10:13], v[172:175], v[206:209], v[10:13]
	s_barrier
; #define PG8_STAGE(bufoff, gbase, voff) do { _Pragma("unroll") for (int _i = 0; _i < 2; ++_i) \
;         __builtin_amdgcn_global_load_lds((const unsigned*)((const char*)(gbase) + (voff)[_i]), (LAS unsigned*)(lds + (bufoff) + ldsw + _i * 8192), 16, 0, 0); } while (0)
; #define PG8_LDA(dst, b, h) do { _Pragma("unroll") for (int m = 0; m < 4; ++m) _Pragma("unroll") for (int k = 0; k < 2; ++k) dst[m][k] = *(const LAS bf16x8*)(lds + PG8_SA(b, h) + aoff + m * 2048 + k * 1024); } while (0)
; #define PG8_LDB(dst, b, h) do { _Pragma("unroll") for (int n = 0; n < 2; ++n) _Pragma("unroll") for (int k = 0; k < 2; ++k) dst[n][k] = *(const LAS bf16x8*)(lds + PG8_SB(b, h) + boff + n * 2048 + k * 1024); } while (0)
; #define PG8_MMA(ai, bj, At, Bt) do { __builtin_amdgcn_s_setprio(1); _Pragma("unroll") for (int m = 0; m < 4; ++m) _Pragma("unroll") for (int n = 0; n < 2; ++n) _Pragma("unroll") for (int k = 0; k < 2; ++k) \
;         acc[ai][bj][m][n] = __builtin_amdgcn_mfma_f32_16x16x32_bf16(Bt[n][k], At[m][k], acc[ai][bj][m][n], 0, 0, 0); __builtin_amdgcn_s_setprio(0); } while (0)
; #define PG8_WAIT_V(n) asm volatile("s_waitcnt vmcnt(" #n ")" ::: "memory")
; #define PG8_WAIT_L(n) asm volatile("s_waitcnt lgkmcnt(" #n ")" ::: "memory")
; #define PG8_BAR __builtin_amdgcn_s_barrier()
; #define PG8_SCHED __builtin_amdgcn_sched_barrier(0)
; template <class Epi>
; __device__ __forceinline__ void gemm_phase(LAS unsigned char* lds, const Gemm g, const StaticOrder& S, const Epi& E) {
;     ...
;             PG8_STAGE(PG8_SB(0, 1), b2 + hstep, voffB);
;             PG8_WAIT_V(6); PG8_BAR; PG8_MMA(1, 1, At, B1); PG8_BAR;
;             PG8_LDB(B0, 1, 0); PG8_SCHED; PG8_LDA(At, 1, 0); PG8_STAGE(PG8_SA(0, 1), a2 + hstep, voffA);
;             PG8_WAIT_L(8); PG8_BAR; PG8_WAIT_L(0); PG8_MMA(0, 0, At, B0); PG8_BAR; PG8_SCHED;
;             PG8_LDB(B1, 1, 1); PG8_STAGE(PG8_SB(1, 0), b3, voffB);
;             PG8_BAR; PG8_WAIT_L(0); PG8_MMA(0, 1, At, B1); PG8_BAR;
;             PG8_LDA(At, 1, 1); PG8_STAGE(PG8_SA(1, 0), a3, voffA);
;             PG8_BAR; PG8_WAIT_L(0); PG8_MMA(1, 0, At, B0); PG8_BAR; PG8_SCHED;
	s_add_u32 s94, s52, 0x60000
	s_addc_u32 s95, s53, 0
	s_add_i32 s71, s93, s54
	v_lshl_add_u64 v[148:149], s[94:95], 0, v[0:1]
	s_mov_b32 m0, s71
	s_nop 0
	global_load_lds_dwordx4 v[148:149], off
	v_lshl_add_u64 v[148:149], s[94:95], 0, v[130:131]
	s_add_i32 m0, s71, 0x2000
	s_nop 0
	global_load_lds_dwordx4 v[148:149], off
	s_waitcnt vmcnt(6)
	s_barrier
	v_mfma_f32_16x16x32_bf16 v[54:57], v[210:213], v[178:181], v[54:57]
	v_mfma_f32_16x16x32_bf16 v[50:53], v[218:221], v[178:181], v[50:53]
	v_mfma_f32_16x16x32_bf16 v[38:41], v[210:213], v[186:189], v[38:41]
	v_mfma_f32_16x16x32_bf16 v[34:37], v[218:221], v[186:189], v[34:37]
	v_mfma_f32_16x16x32_bf16 v[22:25], v[210:213], v[194:197], v[22:25]
	v_mfma_f32_16x16x32_bf16 v[18:21], v[218:221], v[194:197], v[18:21]
	v_mfma_f32_16x16x32_bf16 v[6:9], v[210:213], v[202:205], v[6:9]
	v_mfma_f32_16x16x32_bf16 v[2:5], v[218:221], v[202:205], v[2:5]
	v_mfma_f32_16x16x32_bf16 v[54:57], v[214:217], v[182:185], v[54:57]
	v_mfma_f32_16x16x32_bf16 v[50:53], v[246:249], v[182:185], v[50:53]
	v_mfma_f32_16x16x32_bf16 v[38:41], v[214:217], v[190:193], v[38:41]
	v_mfma_f32_16x16x32_bf16 v[34:37], v[246:249], v[190:193], v[34:37]
	v_mfma_f32_16x16x32_bf16 v[22:25], v[214:217], v[198:201], v[22:25]
	v_mfma_f32_16x16x32_bf16 v[18:21], v[246:249], v[198:201], v[18:21]
	v_mfma_f32_16x16x32_bf16 v[6:9], v[214:217], v[206:209], v[6:9]
	v_mfma_f32_16x16x32_bf16 v[2:5], v[246:249], v[206:209], v[2:5]
	s_add_i32 s71, 0, 0x18000
	v_add_u32_e32 v172, s71, v143
	s_barrier
	ds_read_b128 v[148:151], v172
	ds_read_b128 v[152:155], v172 offset:1024
	ds_read_b128 v[156:159], v172 offset:2048
	ds_read_b128 v[172:175], v172 offset:3072
	s_add_u32 s46, s46, 0x60000
	s_addc_u32 s47, s47, 0
	s_mov_b32 m0, s59
	v_lshl_add_u64 v[210:211], s[46:47], 0, v[0:1]
	ds_read_b128 v[178:181], v147 offset:32768
	ds_read_b128 v[182:185], v147 offset:33792
	ds_read_b128 v[186:189], v147 offset:34816
	ds_read_b128 v[190:193], v147 offset:35840
	ds_read_b128 v[194:197], v147 offset:36864
	ds_read_b128 v[198:201], v147 offset:37888
	ds_read_b128 v[202:205], v147 offset:38912
	ds_read_b128 v[206:209], v147 offset:39936
	global_load_lds_dwordx4 v[210:211], off
	v_lshl_add_u64 v[210:211], s[46:47], 0, v[130:131]
	s_mov_b32 m0, s61
	s_nop 0
	global_load_lds_dwordx4 v[210:211], off
	s_waitcnt lgkmcnt(8)
	s_barrier
	s_waitcnt lgkmcnt(0)
	s_waitcnt lgkmcnt(0)
	v_mfma_f32_16x16x32_bf16 v[126:129], v[148:151], v[178:181], v[126:129]
	v_mfma_f32_16x16x32_bf16 v[122:125], v[156:159], v[178:181], v[122:125]
	v_mfma_f32_16x16x32_bf16 v[110:113], v[148:151], v[186:189], v[110:113]
	v_mfma_f32_16x16x32_bf16 v[106:109], v[156:159], v[186:189], v[106:109]
	v_mfma_f32_16x16x32_bf16 v[94:97], v[148:151], v[194:197], v[94:97]
	v_mfma_f32_16x16x32_bf16 v[90:93], v[156:159], v[194:197], v[90:93]
	v_mfma_f32_16x16x32_bf16 v[78:81], v[148:151], v[202:205], v[78:81]
	v_mfma_f32_16x16x32_bf16 v[74:77], v[156:159], v[202:205], v[74:77]
	v_mfma_f32_16x16x32_bf16 v[126:129], v[152:155], v[182:185], v[126:129]
	v_mfma_f32_16x16x32_bf16 v[122:125], v[172:175], v[182:185], v[122:125]
	v_mfma_f32_16x16x32_bf16 v[110:113], v[152:155], v[190:193], v[110:113]
	v_mfma_f32_16x16x32_bf16 v[106:109], v[172:175], v[190:193], v[106:109]
	v_mfma_f32_16x16x32_bf16 v[94:97], v[152:155], v[198:201], v[94:97]
	v_mfma_f32_16x16x32_bf16 v[90:93], v[172:175], v[198:201], v[90:93]
	v_mfma_f32_16x16x32_bf16 v[78:81], v[152:155], v[206:209], v[78:81]
	v_mfma_f32_16x16x32_bf16 v[74:77], v[172:175], v[206:209], v[74:77]
	s_barrier
	s_add_i32 s93, 0, 0x1c000
	s_add_i32 s46, s71, s54
	v_add_u32_e32 v177, s93, v143
	v_lshl_add_u64 v[140:141], v[140:141], 0, s[28:29]
	s_mov_b32 m0, s46
	ds_read_b128 v[210:213], v177
	ds_read_b128 v[214:217], v177 offset:1024
	ds_read_b128 v[218:221], v177 offset:2048
	ds_read_b128 v[246:249], v177 offset:3072
	global_load_lds_dwordx4 v[140:141], off
	v_lshl_add_u64 v[140:141], v[160:161], 0, s[28:29]
	s_add_i32 m0, s46, 0x2000
	s_nop 0
	global_load_lds_dwordx4 v[140:141], off
	s_barrier
	s_waitcnt lgkmcnt(0)
	s_waitcnt lgkmcnt(0)
	v_mfma_f32_16x16x32_bf16 v[118:121], v[210:213], v[178:181], v[118:121]
	v_mfma_f32_16x16x32_bf16 v[114:117], v[218:221], v[178:181], v[114:117]
	v_mfma_f32_16x16x32_bf16 v[102:105], v[210:213], v[186:189], v[102:105]
	v_mfma_f32_16x16x32_bf16 v[98:101], v[218:221], v[186:189], v[98:101]
	v_mfma_f32_16x16x32_bf16 v[86:89], v[210:213], v[194:197], v[86:89]
	v_mfma_f32_16x16x32_bf16 v[82:85], v[218:221], v[194:197], v[82:85]
	v_mfma_f32_16x16x32_bf16 v[70:73], v[210:213], v[202:205], v[70:73]
	v_mfma_f32_16x16x32_bf16 v[66:69], v[218:221], v[202:205], v[66:69]
	v_mfma_f32_16x16x32_bf16 v[118:121], v[214:217], v[182:185], v[118:121]
	v_mfma_f32_16x16x32_bf16 v[114:117], v[246:249], v[182:185], v[114:117]
	v_mfma_f32_16x16x32_bf16 v[102:105], v[214:217], v[190:193], v[102:105]
	v_mfma_f32_16x16x32_bf16 v[98:101], v[246:249], v[190:193], v[98:101]
	v_mfma_f32_16x16x32_bf16 v[86:89], v[214:217], v[198:201], v[86:89]
	v_mfma_f32_16x16x32_bf16 v[82:85], v[246:249], v[198:201], v[82:85]
	v_mfma_f32_16x16x32_bf16 v[70:73], v[214:217], v[206:209], v[70:73]
	v_mfma_f32_16x16x32_bf16 v[66:69], v[246:249], v[206:209], v[66:69]
	s_mov_b32 m0, s62
	v_lshl_add_u64 v[140:141], v[222:223], 0, s[28:29]
	s_barrier
	ds_read_b128 v[178:181], v147 offset:49152
	ds_read_b128 v[182:185], v147 offset:50176
	ds_read_b128 v[186:189], v147 offset:51200
	ds_read_b128 v[190:193], v147 offset:52224
	ds_read_b128 v[194:197], v147 offset:53248
	ds_read_b128 v[198:201], v147 offset:54272
	ds_read_b128 v[202:205], v147 offset:55296
	ds_read_b128 v[206:209], v147 offset:56320
	global_load_lds_dwordx4 v[140:141], off
	v_lshl_add_u64 v[140:141], v[242:243], 0, s[28:29]
	s_mov_b32 m0, s63
	s_nop 0
	global_load_lds_dwordx4 v[140:141], off
	s_barrier
; __device__ __forceinline__ u64 ss_fix(float ss) { return (u64)(ss * 1048576.f + 0.5f); }
; __device__ __forceinline__ unsigned pk2(float lo, float hi) { unsigned r; asm volatile("v_cvt_pk_bf16_f32 %0, %1, %2" : "=v"(r) : "v"(lo), "v"(hi)); return r; }
; __device__ __forceinline__ float shfl_xor_(float v, int o, int lane) { return shfl_idx(v, lane ^ o); }
; #define PG8_STAGE(bufoff, gbase, voff) do { _Pragma("unroll") for (int _i = 0; _i < 2; ++_i) \
;         __builtin_amdgcn_global_load_lds((const unsigned*)((const char*)(gbase) + (voff)[_i]), (LAS unsigned*)(lds + (bufoff) + ldsw + _i * 8192), 16, 0, 0); } while (0)
; #define PG8_WAIT_V(n) asm volatile("s_waitcnt vmcnt(" #n ")" ::: "memory")
; #define PG8_WAIT_L(n) asm volatile("s_waitcnt lgkmcnt(" #n ")" ::: "memory")
; #define PG8_BAR __builtin_amdgcn_s_barrier()
; #define PG8_SCHED __builtin_amdgcn_sched_barrier(0)
; template <class Epi>
; __device__ __forceinline__ void gemm_phase(LAS unsigned char* lds, const Gemm g, const StaticOrder& S, const Epi& E) {
;     ...
;             PG8_BAR; PG8_WAIT_L(0); PG8_MMA(1, 0, At, B0); PG8_BAR; PG8_SCHED;
;             PG8_STAGE(PG8_SB(1, 1), b3 + hstep, voffB);
;             PG8_WAIT_V(6); PG8_BAR; PG8_MMA(1, 1, At, B1); PG8_BAR;
;     __device__ __forceinline__ void operator()(const f32x4 (&acc)[2][2][4][2], const Unit& u, int wr, int wc, int fr, int fq) const {
;         const int row0 = u.pm * BM + wr * 64 + fr, col0 = u.pn * BM + wc * 32 + 4 * fq, lane = fr | (fq << 4);
; #pragma unroll
;         for (int ai = 0; ai < 2; ++ai)
; #pragma unroll
;             for (int m = 0; m < 4; ++m) { const int row = row0 + ai * HALF + m * 16; bf16_t* xbp = xb + (size_t)row * ldc + col0;
;                 float ss = 0.f;
; #pragma unroll
;                 for (int bj = 0; bj < 2; ++bj)
; #pragma unroll
;                     for (int n = 0; n < 2; ++n) { u32x2* pp = (u32x2*)(xbp + bj * HALF + n * 16); float o[4]; unpack4(*pp, o);
;                         u32x2 w; w.x = pk2(o[0] + acc[ai][bj][m][n][0], o[1] + acc[ai][bj][m][n][1]); w.y = pk2(o[2] + acc[ai][bj][m][n][2], o[3] + acc[ai][bj][m][n][3]); *pp = w;
;                         unpack4(w, o); ss += o[0] * o[0] + o[1] * o[1] + o[2] * o[2] + o[3] * o[3]; }
;                 ss += shfl_xor_(ss, 16, lane); ss += shfl_xor_(ss, 32, lane);
;                 if (fq == 0) atomicAdd(rss + row, ss_fix(ss)); }
	s_waitcnt lgkmcnt(0)
	s_waitcnt lgkmcnt(0)
	s_nop 0
	v_mfma_f32_16x16x32_bf16 v[62:65], v[148:151], v[178:181], v[62:65]
	v_mfma_f32_16x16x32_bf16 v[58:61], v[156:159], v[178:181], v[58:61]
	v_mfma_f32_16x16x32_bf16 v[46:49], v[148:151], v[186:189], v[46:49]
	v_mfma_f32_16x16x32_bf16 v[42:45], v[156:159], v[186:189], v[42:45]
	v_mfma_f32_16x16x32_bf16 v[30:33], v[148:151], v[194:197], v[30:33]
	v_mfma_f32_16x16x32_bf16 v[26:29], v[156:159], v[194:197], v[26:29]
	v_mfma_f32_16x16x32_bf16 v[14:17], v[148:151], v[202:205], v[14:17]
	v_mfma_f32_16x16x32_bf16 v[10:13], v[156:159], v[202:205], v[10:13]
	v_mfma_f32_16x16x32_bf16 v[62:65], v[152:155], v[182:185], v[62:65]
	v_mfma_f32_16x16x32_bf16 v[58:61], v[172:175], v[182:185], v[58:61]
	v_mfma_f32_16x16x32_bf16 v[46:49], v[152:155], v[190:193], v[46:49]
	v_mfma_f32_16x16x32_bf16 v[42:45], v[172:175], v[190:193], v[42:45]
	v_mfma_f32_16x16x32_bf16 v[30:33], v[152:155], v[198:201], v[30:33]
	v_mfma_f32_16x16x32_bf16 v[26:29], v[172:175], v[198:201], v[26:29]
	v_mfma_f32_16x16x32_bf16 v[14:17], v[152:155], v[206:209], v[14:17]
	v_mfma_f32_16x16x32_bf16 v[10:13], v[172:175], v[206:209], v[10:13]
	s_barrier
	s_add_u32 s46, s52, 0x60080
	s_addc_u32 s47, s53, 0
	s_add_i32 s52, s93, s54
	v_lshl_add_u64 v[140:141], s[46:47], 0, v[0:1]
	s_mov_b32 m0, s52
	s_nop 0
	global_load_lds_dwordx4 v[140:141], off
	v_lshl_add_u64 v[140:141], s[46:47], 0, v[130:131]
	s_add_i32 m0, s52, 0x2000
	s_nop 0
	global_load_lds_dwordx4 v[140:141], off
	s_waitcnt vmcnt(6)
	s_barrier
	v_mfma_f32_16x16x32_bf16 v[54:57], v[210:213], v[178:181], v[54:57]
	v_mfma_f32_16x16x32_bf16 v[50:53], v[218:221], v[178:181], v[50:53]
	v_mfma_f32_16x16x32_bf16 v[38:41], v[210:213], v[186:189], v[38:41]
	v_mfma_f32_16x16x32_bf16 v[34:37], v[218:221], v[186:189], v[34:37]
	v_mfma_f32_16x16x32_bf16 v[22:25], v[210:213], v[194:197], v[22:25]
	v_mfma_f32_16x16x32_bf16 v[18:21], v[218:221], v[194:197], v[18:21]
	v_mfma_f32_16x16x32_bf16 v[6:9], v[210:213], v[202:205], v[6:9]
	v_mfma_f32_16x16x32_bf16 v[2:5], v[218:221], v[202:205], v[2:5]
	v_mfma_f32_16x16x32_bf16 v[54:57], v[214:217], v[182:185], v[54:57]
	v_mfma_f32_16x16x32_bf16 v[50:53], v[246:249], v[182:185], v[50:53]
	v_mfma_f32_16x16x32_bf16 v[38:41], v[214:217], v[190:193], v[38:41]
	v_mfma_f32_16x16x32_bf16 v[34:37], v[246:249], v[190:193], v[34:37]
	v_mfma_f32_16x16x32_bf16 v[22:25], v[214:217], v[198:201], v[22:25]
	v_mfma_f32_16x16x32_bf16 v[18:21], v[246:249], v[198:201], v[18:21]
	v_mfma_f32_16x16x32_bf16 v[6:9], v[214:217], v[206:209], v[6:9]
	v_mfma_f32_16x16x32_bf16 v[2:5], v[246:249], v[206:209], v[2:5]
	s_add_i32 s70, s70, 2
	s_add_u32 s50, s50, 0x100
	s_addc_u32 s51, s51, 0
	s_cmp_gt_u32 s70, 21
	s_barrier
	s_cbranch_scc0 .LBB0_258
	s_setprio 0
	s_add_u32 s46, s68, 0xffffff00
	s_addc_u32 s47, s69, -1
	s_and_b64 vcc, exec, s[0:1]
	s_cbranch_vccz .LBB0_277
	v_lshl_add_u32 v140, s66, 8, v142
	v_ashrrev_i32_e32 v141, 31, v140
	v_readlane_b32 s0, v252, 51
	v_lshl_or_b32 v138, s65, 8, v144
	v_lshlrev_b64 v[136:137], 11, v[140:141]
	v_readlane_b32 s1, v252, 52
	v_ashrrev_i32_e32 v139, 31, v138
	s_nop 0
	v_lshl_add_u64 v[136:137], s[0:1], 0, v[136:137]
	v_lshl_add_u64 v[136:137], v[138:139], 1, v[136:137]
	global_load_dwordx2 v[148:149], v[136:137], off
	s_waitcnt vmcnt(0)
	v_lshlrev_b32_e32 v150, 16, v148
	v_and_b32_e32 v148, 0xffff0000, v148
	v_lshlrev_b32_e32 v151, 16, v149
	v_and_b32_e32 v149, 0xffff0000, v149
	v_add_f32_e32 v126, v126, v150
	v_add_f32_e32 v127, v127, v148
	v_add_f32_e32 v128, v128, v151
	v_add_f32_e32 v129, v129, v149
	v_cvt_pk_bf16_f32 v126, v126, v127
	v_cvt_pk_bf16_f32 v127, v128, v129
	global_load_dwordx2 v[128:129], v[136:137], off offset:32
	s_waitcnt vmcnt(0)
	v_lshlrev_b32_e32 v148, 16, v128
	v_and_b32_e32 v128, 0xffff0000, v128
	v_lshlrev_b32_e32 v149, 16, v129
	v_and_b32_e32 v129, 0xffff0000, v129
	v_add_f32_e32 v122, v122, v148
	v_add_f32_e32 v123, v123, v128
	v_add_f32_e32 v124, v124, v149
	v_add_f32_e32 v125, v125, v129
	global_store_dwordx2 v[136:137], v[126:127], off
	v_cvt_pk_bf16_f32 v122, v122, v123
	v_cvt_pk_bf16_f32 v123, v124, v125
	global_load_dwordx2 v[124:125], v[136:137], off offset:256
	s_waitcnt vmcnt(0)
	v_lshlrev_b32_e32 v128, 16, v124
	v_and_b32_e32 v124, 0xffff0000, v124
	v_lshlrev_b32_e32 v129, 16, v125
	v_and_b32_e32 v125, 0xffff0000, v125
	v_add_f32_e32 v118, v118, v128
	v_add_f32_e32 v119, v119, v124
	v_add_f32_e32 v120, v120, v129
	v_add_f32_e32 v121, v121, v125
	global_store_dwordx2 v[136:137], v[122:123], off offset:32
	v_cvt_pk_bf16_f32 v118, v118, v119
	v_cvt_pk_bf16_f32 v119, v120, v121
	global_load_dwordx2 v[120:121], v[136:137], off offset:288
	v_and_b32_e32 v125, 0xffff0000, v126
	v_lshlrev_b32_e32 v124, 16, v126
	v_mul_f32_e32 v125, v125, v125
	v_fmac_f32_e32 v125, v124, v124
	v_lshlrev_b32_e32 v124, 16, v122
	v_and_b32_e32 v122, 0xffff0000, v122
	v_lshlrev_b32_e32 v126, 16, v127
	v_mul_f32_e32 v122, v122, v122
	v_fmac_f32_e32 v125, v126, v126
	v_lshlrev_b32_e32 v126, 16, v123
	v_fmac_f32_e32 v122, v124, v124
	v_and_b32_e32 v123, 0xffff0000, v123
	v_fmac_f32_e32 v122, v126, v126
	v_fmac_f32_e32 v122, v123, v123
	global_store_dwordx2 v[136:137], v[118:119], off offset:256
	v_lshlrev_b32_e32 v123, 16, v118
	v_and_b32_e32 v118, 0xffff0000, v118
	v_mul_f32_e32 v118, v118, v118
	v_and_b32_e32 v127, 0xffff0000, v127
	v_lshlrev_b32_e32 v124, 16, v119
	v_fmac_f32_e32 v118, v123, v123
	v_fmac_f32_e32 v125, v127, v127
	v_and_b32_e32 v119, 0xffff0000, v119
	v_fmac_f32_e32 v118, v124, v124
	v_add_f32_e32 v122, v125, v122
	v_fmac_f32_e32 v118, v119, v119
	v_add_f32_e32 v118, v122, v118
	s_waitcnt vmcnt(0)
	v_lshlrev_b32_e32 v119, 16, v120
	v_and_b32_e32 v120, 0xffff0000, v120
	v_lshlrev_b32_e32 v122, 16, v121
	v_and_b32_e32 v121, 0xffff0000, v121
	v_add_f32_e32 v114, v114, v119
	v_add_f32_e32 v115, v115, v120
	v_add_f32_e32 v117, v117, v121
	v_add_f32_e32 v116, v116, v122
	v_cvt_pk_bf16_f32 v114, v114, v115
	v_cvt_pk_bf16_f32 v115, v116, v117
	global_store_dwordx2 v[136:137], v[114:115], off offset:288
	v_and_b32_e32 v117, 0xffff0000, v114
	v_lshlrev_b32_e32 v116, 16, v114
	v_mul_f32_e32 v117, v117, v117
	v_lshlrev_b32_e32 v119, 16, v115
	v_fmac_f32_e32 v117, v116, v116
	v_and_b32_e32 v120, 0xffff0000, v115
	v_fmac_f32_e32 v117, v119, v119
	v_fmac_f32_e32 v117, v120, v120
	v_add_f32_e32 v116, v118, v117
	ds_bpermute_b32 v117, v145, v116
	v_lshl_add_u64 v[114:115], v[140:141], 3, s[76:77]
	s_waitcnt lgkmcnt(0)
	v_add_f32_e32 v116, v116, v117
	ds_bpermute_b32 v117, v146, v116
	s_and_saveexec_b64 s[0:1], s[40:41]
	v_readlane_b32 s94, v254, 32
	s_movk_i32 s93, 0x1000
	v_readlane_b32 s95, v254, 33
	s_cbranch_execz .LBB0_262
	s_waitcnt lgkmcnt(0)
	v_add_f32_e32 v116, v116, v117
	s_mov_b32 s46, 0x49800000
	v_fma_f32 v116, v116, s46, 0.5
	v_trunc_f32_e32 v116, v116
	v_mul_f32_e32 v117, 0x2f800000, v116
	v_floor_f32_e32 v117, v117
	v_fmac_f32_e32 v116, 0xcf800000, v117
	v_cvt_u32_f32_e32 v116, v116
	v_cvt_u32_f32_e32 v117, v117
	global_atomic_add_x2 v[114:115], v[116:117], off

; #define PG8_STAGE(bufoff, gbase, voff) do { _Pragma("unroll") for (int _i = 0; _i < 2; ++_i) \
;         __builtin_amdgcn_global_load_lds((const unsigned*)((const char*)(gbase) + (voff)[_i]), (LAS unsigned*)(lds + (bufoff) + ldsw + _i * 8192), 16, 0, 0); } while (0)
; #define PG8_LDA(dst, b, h) do { _Pragma("unroll") for (int m = 0; m < 4; ++m) _Pragma("unroll") for (int k = 0; k < 2; ++k) dst[m][k] = *(const LAS bf16x8*)(lds + PG8_SA(b, h) + aoff + m * 2048 + k * 1024); } while (0)
; #define PG8_LDB(dst, b, h) do { _Pragma("unroll") for (int n = 0; n < 2; ++n) _Pragma("unroll") for (int k = 0; k < 2; ++k) dst[n][k] = *(const LAS bf16x8*)(lds + PG8_SB(b, h) + boff + n * 2048 + k * 1024); } while (0)
; #define PG8_MMA(ai, bj, At, Bt) do { __builtin_amdgcn_s_setprio(1); _Pragma("unroll") for (int m = 0; m < 4; ++m) _Pragma("unroll") for (int n = 0; n < 2; ++n) _Pragma("unroll") for (int k = 0; k < 2; ++k) \
;         acc[ai][bj][m][n] = __builtin_amdgcn_mfma_f32_16x16x32_bf16(Bt[n][k], At[m][k], acc[ai][bj][m][n], 0, 0, 0); __builtin_amdgcn_s_setprio(0); } while (0)
; #define PG8_WAIT_L(n) asm volatile("s_waitcnt lgkmcnt(" #n ")" ::: "memory")
; #define PG8_BAR __builtin_amdgcn_s_barrier()
; #define PG8_SCHED __builtin_amdgcn_sched_barrier(0)
; template <class Epi>
; __device__ __forceinline__ void gemm_phase(LAS unsigned char* lds, const Gemm g, const StaticOrder& S, const Epi& E) {
;     ...
;             PG8_LDB(B0, 0, 0); PG8_SCHED; PG8_LDA(At, 0, 0); PG8_STAGE(PG8_SA(1, 1), a1 + hstep, voffA);
;             PG8_WAIT_L(8); PG8_BAR; PG8_WAIT_L(0); PG8_MMA(0, 0, At, B0); PG8_BAR; PG8_SCHED;
;             PG8_LDB(B1, 0, 1); PG8_STAGE(PG8_SB(0, 0), b2, voffB);
;             PG8_BAR; PG8_WAIT_L(0); PG8_MMA(0, 1, At, B1); PG8_BAR;
;             PG8_LDA(At, 0, 1); PG8_STAGE(PG8_SA(0, 0), a2, voffA);
;             PG8_BAR; PG8_WAIT_L(0); PG8_MMA(1, 0, At, B0); PG8_BAR; PG8_SCHED;
;             PG8_STAGE(PG8_SB(0, 1), b2 + hstep, voffB);
.Lprio_505:
.LBB0_505:
	s_add_u32 s48, s46, 0xfffc0080
	s_addc_u32 s49, s47, -1
	s_add_i32 s63, 0, 0x10000
	v_add_u32_e32 v152, s63, v171
	ds_read_b128 v[140:143], v152
	ds_read_b128 v[144:147], v152 offset:1024
	ds_read_b128 v[148:151], v152 offset:2048
	ds_read_b128 v[152:155], v152 offset:3072
	s_cmp_eq_u32 s62, 12
	s_cselect_b32 s51, s39, s49
	s_cselect_b32 s50, s58, s48
	s_cselect_b32 s49, s1, s61
	s_cselect_b32 s48, s59, s60
	v_lshl_add_u64 v[160:161], s[46:47], 0, v[136:137]
	s_add_i32 m0, s24, 0xc000
	ds_read_b128 v[156:159], v179
	ds_read_b128 v[180:183], v179 offset:1024
	ds_read_b128 v[184:187], v179 offset:2048
	ds_read_b128 v[188:191], v179 offset:3072
	ds_read_b128 v[192:195], v179 offset:4096
	ds_read_b128 v[196:199], v179 offset:5120
	ds_read_b128 v[200:203], v179 offset:6144
	ds_read_b128 v[204:207], v179 offset:7168
	global_load_lds_dwordx4 v[160:161], off
	v_lshl_add_u64 v[160:161], s[46:47], 0, v[138:139]
	s_add_i32 m0, s24, 0xe000
	s_nop 0
	global_load_lds_dwordx4 v[160:161], off
	s_waitcnt lgkmcnt(8)
	s_barrier
	s_waitcnt lgkmcnt(0)
	s_waitcnt lgkmcnt(0)
	v_mfma_f32_16x16x32_bf16 v[126:129], v[140:143], v[156:159], v[126:129]
	v_mfma_f32_16x16x32_bf16 v[122:125], v[148:151], v[156:159], v[122:125]
	v_mfma_f32_16x16x32_bf16 v[110:113], v[140:143], v[184:187], v[110:113]
	v_mfma_f32_16x16x32_bf16 v[106:109], v[148:151], v[184:187], v[106:109]
	v_mfma_f32_16x16x32_bf16 v[94:97], v[140:143], v[192:195], v[94:97]
	v_mfma_f32_16x16x32_bf16 v[90:93], v[148:151], v[192:195], v[90:93]
	v_mfma_f32_16x16x32_bf16 v[78:81], v[140:143], v[200:203], v[78:81]
	v_mfma_f32_16x16x32_bf16 v[74:77], v[148:151], v[200:203], v[74:77]
	v_mfma_f32_16x16x32_bf16 v[126:129], v[144:147], v[180:183], v[126:129]
	v_mfma_f32_16x16x32_bf16 v[122:125], v[152:155], v[180:183], v[122:125]
	v_mfma_f32_16x16x32_bf16 v[110:113], v[144:147], v[188:191], v[110:113]
	v_mfma_f32_16x16x32_bf16 v[106:109], v[152:155], v[188:191], v[106:109]
	v_mfma_f32_16x16x32_bf16 v[94:97], v[144:147], v[196:199], v[94:97]
	v_mfma_f32_16x16x32_bf16 v[90:93], v[152:155], v[196:199], v[90:93]
	v_mfma_f32_16x16x32_bf16 v[78:81], v[144:147], v[204:207], v[78:81]
	v_mfma_f32_16x16x32_bf16 v[74:77], v[152:155], v[204:207], v[74:77]
	s_barrier
	s_add_i32 s66, 0, 0x14000
	v_add_u32_e32 v160, s66, v171
	s_add_i32 s63, s63, s3
	ds_read_b128 v[208:211], v160
	ds_read_b128 v[212:215], v160 offset:1024
	ds_read_b128 v[216:219], v160 offset:2048
	ds_read_b128 v[220:223], v160 offset:3072
	v_lshl_add_u64 v[160:161], s[48:49], 0, v[0:1]
	s_mov_b32 m0, s63
	v_lshl_add_u64 v[172:173], s[48:49], 0, v[130:131]
	global_load_lds_dwordx4 v[160:161], off
	s_add_i32 m0, s63, 0x2000
	s_nop 0
	global_load_lds_dwordx4 v[172:173], off
	s_barrier
	s_waitcnt lgkmcnt(0)
	s_waitcnt lgkmcnt(0)
	v_mfma_f32_16x16x32_bf16 v[118:121], v[208:211], v[156:159], v[118:121]
	v_mfma_f32_16x16x32_bf16 v[114:117], v[216:219], v[156:159], v[114:117]
	v_mfma_f32_16x16x32_bf16 v[102:105], v[208:211], v[184:187], v[102:105]
	v_mfma_f32_16x16x32_bf16 v[98:101], v[216:219], v[184:187], v[98:101]
	v_mfma_f32_16x16x32_bf16 v[86:89], v[208:211], v[192:195], v[86:89]
	v_mfma_f32_16x16x32_bf16 v[82:85], v[216:219], v[192:195], v[82:85]
	v_mfma_f32_16x16x32_bf16 v[70:73], v[208:211], v[200:203], v[70:73]
	v_mfma_f32_16x16x32_bf16 v[66:69], v[216:219], v[200:203], v[66:69]
	v_mfma_f32_16x16x32_bf16 v[118:121], v[212:215], v[180:183], v[118:121]
	v_mfma_f32_16x16x32_bf16 v[114:117], v[220:223], v[180:183], v[114:117]
	v_mfma_f32_16x16x32_bf16 v[102:105], v[212:215], v[188:191], v[102:105]
	v_mfma_f32_16x16x32_bf16 v[98:101], v[220:223], v[188:191], v[98:101]
	v_mfma_f32_16x16x32_bf16 v[86:89], v[212:215], v[196:199], v[86:89]
	v_mfma_f32_16x16x32_bf16 v[82:85], v[220:223], v[196:199], v[82:85]
	v_mfma_f32_16x16x32_bf16 v[70:73], v[212:215], v[204:207], v[70:73]
	v_mfma_f32_16x16x32_bf16 v[66:69], v[220:223], v[204:207], v[66:69]
	s_mov_b32 m0, s24
	v_lshl_add_u64 v[174:175], s[50:51], 0, v[134:135]
	s_barrier
	ds_read_b128 v[156:159], v179 offset:16384
	ds_read_b128 v[180:183], v179 offset:17408
	ds_read_b128 v[184:187], v179 offset:18432
	ds_read_b128 v[188:191], v179 offset:19456
	ds_read_b128 v[192:195], v179 offset:20480
	ds_read_b128 v[196:199], v179 offset:21504
	ds_read_b128 v[200:203], v179 offset:22528
	ds_read_b128 v[204:207], v179 offset:23552
	global_load_lds_dwordx4 v[174:175], off
	v_lshl_add_u64 v[176:177], s[50:51], 0, v[132:133]
	s_mov_b32 m0, s26
	s_nop 0
	global_load_lds_dwordx4 v[176:177], off
	s_barrier
	s_waitcnt lgkmcnt(0)
	s_waitcnt lgkmcnt(0)
	s_nop 0
	v_mfma_f32_16x16x32_bf16 v[62:65], v[140:143], v[156:159], v[62:65]
	v_mfma_f32_16x16x32_bf16 v[58:61], v[148:151], v[156:159], v[58:61]
	v_mfma_f32_16x16x32_bf16 v[46:49], v[140:143], v[184:187], v[46:49]
	v_mfma_f32_16x16x32_bf16 v[42:45], v[148:151], v[184:187], v[42:45]
	v_mfma_f32_16x16x32_bf16 v[30:33], v[140:143], v[192:195], v[30:33]
	v_mfma_f32_16x16x32_bf16 v[26:29], v[148:151], v[192:195], v[26:29]
	v_mfma_f32_16x16x32_bf16 v[14:17], v[140:143], v[200:203], v[14:17]
	v_mfma_f32_16x16x32_bf16 v[10:13], v[148:151], v[200:203], v[10:13]
	v_mfma_f32_16x16x32_bf16 v[62:65], v[144:147], v[180:183], v[62:65]
	v_mfma_f32_16x16x32_bf16 v[58:61], v[152:155], v[180:183], v[58:61]
	v_mfma_f32_16x16x32_bf16 v[46:49], v[144:147], v[188:191], v[46:49]
	v_mfma_f32_16x16x32_bf16 v[42:45], v[152:155], v[188:191], v[42:45]
	v_mfma_f32_16x16x32_bf16 v[30:33], v[144:147], v[196:199], v[30:33]
	v_mfma_f32_16x16x32_bf16 v[26:29], v[152:155], v[196:199], v[26:29]
	v_mfma_f32_16x16x32_bf16 v[14:17], v[144:147], v[204:207], v[14:17]
	v_mfma_f32_16x16x32_bf16 v[10:13], v[152:155], v[204:207], v[10:13]
	s_barrier
	s_add_u32 s64, s48, 0x40000
	s_addc_u32 s65, s49, 0
	s_add_i32 s63, s66, s3
	v_lshl_add_u64 v[140:141], s[64:65], 0, v[0:1]
	s_mov_b32 m0, s63
	s_nop 0
	global_load_lds_dwordx4 v[140:141], off
	v_lshl_add_u64 v[140:141], s[64:65], 0, v[130:131]
	s_add_i32 m0, s63, 0x2000
	s_nop 0
	global_load_lds_dwordx4 v[140:141], off
	s_cmp_lg_u32 s62, -2
	s_cbranch_scc1 .Lrx_s0_std
	s_cmp_lt_u32 s55, 2
	s_cbranch_scc1 .Lrx_s0_std
	s_waitcnt vmcnt(24)
	s_branch .Lrx_s0_done
